# v40 + removed mid-block setprio pairs and redundant post-barrier lgkmcnt(0) waits in GEMM K-loops
# speedup vs baseline: 1.0146x; 1.0035x over previous
.LBB0_113:
	s_add_u32 s20, s0, 0x100
	s_addc_u32 s21, s1, 0
	s_ashr_i32 s37, s36, 31
	s_lshl_b64 s[38:39], s[36:37], 20
	s_add_u32 s40, s16, s38
	s_addc_u32 s41, s17, s39
	s_and_b64 s[38:39], s[62:63], exec
	s_cselect_b32 s25, s41, s5
	s_cselect_b32 s37, s40, s4
	s_ashr_i32 s29, s28, 31
	s_lshl_b64 s[38:39], s[28:29], 20
	s_add_u32 s38, s3, s38
	s_addc_u32 s39, s22, s39
	s_and_b64 s[42:43], s[62:63], exec
	s_cselect_b32 s29, s39, s1
	s_cselect_b32 s64, s38, s0
	s_add_u32 s0, s4, 0x80080
	s_addc_u32 s1, s5, 0
	v_lshl_add_u64 v[138:139], s[0:1], 0, v[134:135]
	v_lshl_add_u64 v[140:141], s[0:1], 0, v[136:137]
	s_mov_b32 s65, -2
	s_mov_b64 s[0:1], 0
	s_add_u32 s42, s4, s0
	s_addc_u32 s43, s5, s1
	s_add_u32 s42, s42, 0x100
	s_addc_u32 s43, s43, 0
	s_add_u32 s66, s20, s0
	s_addc_u32 s67, s21, s1
	s_add_i32 s70, 0, 0x10000
	s_cmpk_eq_i32 s0, 0xf00
	s_cselect_b32 s45, s25, s43
	s_cselect_b32 s44, s37, s42
	v_add_u32_e32 v155, s70, v151
	s_cselect_b32 s43, s29, s67
	s_cselect_b32 s42, s64, s66
	s_add_i32 s71, 0, 0x14000
	ds_read_b128 v[142:145], v155
	ds_read_b128 v[146:149], v155 offset:1024
	ds_read_b128 v[156:159], v155 offset:2048
	ds_read_b128 v[160:163], v155 offset:3072
	v_add_u32_e32 v155, s71, v151
	ds_read_b128 v[164:167], v155
	ds_read_b128 v[168:171], v155 offset:1024
	ds_read_b128 v[172:175], v155 offset:2048
	ds_read_b128 v[176:179], v155 offset:3072
	v_lshl_add_u64 v[222:223], v[138:139], 0, s[0:1]
	s_add_i32 m0, s46, 0xc000
	ds_read_b128 v[180:183], v154
	ds_read_b128 v[184:187], v154 offset:1024
	ds_read_b128 v[188:191], v154 offset:2048
	ds_read_b128 v[192:195], v154 offset:3072
	ds_read_b128 v[196:199], v154 offset:4096
	ds_read_b128 v[210:213], v154 offset:5120
	ds_read_b128 v[214:217], v154 offset:6144
	ds_read_b128 v[218:221], v154 offset:7168
	global_load_lds_dwordx4 v[222:223], off
	v_lshl_add_u64 v[222:223], v[140:141], 0, s[0:1]
	s_add_i32 m0, s46, 0xe000
	s_nop 0
	global_load_lds_dwordx4 v[222:223], off
	s_waitcnt vmcnt(8)
	s_waitcnt lgkmcnt(0)
	s_barrier
	s_setprio 1
	v_mfma_f32_16x16x32_bf16 v[124:127], v[142:145], v[180:183], 0
	v_mfma_f32_16x16x32_bf16 v[120:123], v[156:159], v[180:183], 0
	v_mfma_f32_16x16x32_bf16 v[116:119], v[142:145], v[188:191], 0
	v_mfma_f32_16x16x32_bf16 v[112:115], v[156:159], v[188:191], 0
	v_mfma_f32_16x16x32_bf16 v[108:111], v[142:145], v[196:199], 0
	v_mfma_f32_16x16x32_bf16 v[104:107], v[156:159], v[196:199], 0
	v_mfma_f32_16x16x32_bf16 v[100:103], v[142:145], v[214:217], 0
	v_mfma_f32_16x16x32_bf16 v[96:99], v[156:159], v[214:217], 0
	v_mfma_f32_16x16x32_bf16 v[124:127], v[146:149], v[184:187], v[124:127]
	v_mfma_f32_16x16x32_bf16 v[120:123], v[160:163], v[184:187], v[120:123]
	v_mfma_f32_16x16x32_bf16 v[116:119], v[146:149], v[192:195], v[116:119]
	v_mfma_f32_16x16x32_bf16 v[112:115], v[160:163], v[192:195], v[112:115]
	v_mfma_f32_16x16x32_bf16 v[108:111], v[146:149], v[210:213], v[108:111]
	v_mfma_f32_16x16x32_bf16 v[104:107], v[160:163], v[210:213], v[104:107]
	v_mfma_f32_16x16x32_bf16 v[100:103], v[146:149], v[218:221], v[100:103]
	v_mfma_f32_16x16x32_bf16 v[96:99], v[160:163], v[218:221], v[96:99]
	v_mfma_f32_16x16x32_bf16 v[92:95], v[164:167], v[180:183], 0
	v_mfma_f32_16x16x32_bf16 v[88:91], v[172:175], v[180:183], 0
	v_mfma_f32_16x16x32_bf16 v[84:87], v[164:167], v[188:191], 0
	v_mfma_f32_16x16x32_bf16 v[80:83], v[172:175], v[188:191], 0
	v_mfma_f32_16x16x32_bf16 v[76:79], v[164:167], v[196:199], 0
	v_mfma_f32_16x16x32_bf16 v[72:75], v[172:175], v[196:199], 0
	v_mfma_f32_16x16x32_bf16 v[68:71], v[164:167], v[214:217], 0
	v_mfma_f32_16x16x32_bf16 v[64:67], v[172:175], v[214:217], 0
	v_mfma_f32_16x16x32_bf16 v[92:95], v[168:171], v[184:187], v[92:95]
	v_mfma_f32_16x16x32_bf16 v[88:91], v[176:179], v[184:187], v[88:91]
	v_mfma_f32_16x16x32_bf16 v[84:87], v[168:171], v[192:195], v[84:87]
	v_mfma_f32_16x16x32_bf16 v[80:83], v[176:179], v[192:195], v[80:83]
	v_mfma_f32_16x16x32_bf16 v[76:79], v[168:171], v[210:213], v[76:79]
	v_mfma_f32_16x16x32_bf16 v[72:75], v[176:179], v[210:213], v[72:75]
	v_mfma_f32_16x16x32_bf16 v[68:71], v[168:171], v[218:221], v[68:71]
	v_mfma_f32_16x16x32_bf16 v[64:67], v[176:179], v[218:221], v[64:67]
	s_setprio 0
	s_barrier
	s_add_i32 s66, s70, s2
	v_lshl_add_u64 v[222:223], s[42:43], 0, v[204:205]
	s_mov_b32 m0, s66
	ds_read_b128 v[180:183], v154 offset:16384
	ds_read_b128 v[184:187], v154 offset:17408
	ds_read_b128 v[188:191], v154 offset:18432
	ds_read_b128 v[192:195], v154 offset:19456
	ds_read_b128 v[196:199], v154 offset:20480
	ds_read_b128 v[210:213], v154 offset:21504
	ds_read_b128 v[214:217], v154 offset:22528
	ds_read_b128 v[218:221], v154 offset:23552
	global_load_lds_dwordx4 v[222:223], off
	s_add_i32 m0, s66, 0x2000
	s_add_u32 s66, s42, 0x80000
	v_lshl_add_u64 v[224:225], s[42:43], 0, v[128:129]
	s_addc_u32 s67, s43, 0
	s_add_i32 s70, s71, s2
	global_load_lds_dwordx4 v[224:225], off
	v_lshl_add_u64 v[226:227], s[66:67], 0, v[204:205]
	s_mov_b32 m0, s70
	v_lshl_add_u64 v[228:229], s[44:45], 0, v[130:131]
	global_load_lds_dwordx4 v[226:227], off
	v_lshl_add_u64 v[226:227], s[66:67], 0, v[128:129]
	s_add_i32 m0, s70, 0x2000
	s_nop 0
	global_load_lds_dwordx4 v[226:227], off
	v_lshl_add_u64 v[226:227], s[44:45], 0, v[132:133]
	s_mov_b32 m0, s46
	s_nop 0
	global_load_lds_dwordx4 v[226:227], off
	s_mov_b32 m0, s47
	s_nop 0
	global_load_lds_dwordx4 v[228:229], off
	s_waitcnt vmcnt(8)
	s_waitcnt lgkmcnt(0)
	s_barrier
	s_setprio 1
	v_mfma_f32_16x16x32_bf16 v[60:63], v[142:145], v[180:183], 0
	v_mfma_f32_16x16x32_bf16 v[56:59], v[156:159], v[180:183], 0
	v_mfma_f32_16x16x32_bf16 v[52:55], v[142:145], v[188:191], 0
	v_mfma_f32_16x16x32_bf16 v[48:51], v[156:159], v[188:191], 0
	v_mfma_f32_16x16x32_bf16 v[44:47], v[142:145], v[196:199], 0
	v_mfma_f32_16x16x32_bf16 v[40:43], v[156:159], v[196:199], 0
	v_mfma_f32_16x16x32_bf16 v[36:39], v[142:145], v[214:217], 0
	v_mfma_f32_16x16x32_bf16 v[32:35], v[156:159], v[214:217], 0
	v_mfma_f32_16x16x32_bf16 v[60:63], v[146:149], v[184:187], v[60:63]
	v_mfma_f32_16x16x32_bf16 v[56:59], v[160:163], v[184:187], v[56:59]
	v_mfma_f32_16x16x32_bf16 v[52:55], v[146:149], v[192:195], v[52:55]
	v_mfma_f32_16x16x32_bf16 v[48:51], v[160:163], v[192:195], v[48:51]
	v_mfma_f32_16x16x32_bf16 v[44:47], v[146:149], v[210:213], v[44:47]
	v_mfma_f32_16x16x32_bf16 v[40:43], v[160:163], v[210:213], v[40:43]
	v_mfma_f32_16x16x32_bf16 v[36:39], v[146:149], v[218:221], v[36:39]
	v_mfma_f32_16x16x32_bf16 v[32:35], v[160:163], v[218:221], v[32:35]
	v_mfma_f32_16x16x32_bf16 v[28:31], v[164:167], v[180:183], 0
	v_mfma_f32_16x16x32_bf16 v[24:27], v[172:175], v[180:183], 0
	v_mfma_f32_16x16x32_bf16 v[20:23], v[164:167], v[188:191], 0
	v_mfma_f32_16x16x32_bf16 v[16:19], v[172:175], v[188:191], 0
	v_mfma_f32_16x16x32_bf16 v[12:15], v[164:167], v[196:199], 0
	v_mfma_f32_16x16x32_bf16 v[8:11], v[172:175], v[196:199], 0
	v_mfma_f32_16x16x32_bf16 v[4:7], v[164:167], v[214:217], 0
	v_mfma_f32_16x16x32_bf16 v[0:3], v[172:175], v[214:217], 0
	v_mfma_f32_16x16x32_bf16 v[28:31], v[168:171], v[184:187], v[28:31]
	v_mfma_f32_16x16x32_bf16 v[24:27], v[176:179], v[184:187], v[24:27]
	v_mfma_f32_16x16x32_bf16 v[20:23], v[168:171], v[192:195], v[20:23]
	v_mfma_f32_16x16x32_bf16 v[16:19], v[176:179], v[192:195], v[16:19]
	v_mfma_f32_16x16x32_bf16 v[12:15], v[168:171], v[210:213], v[12:15]
	v_mfma_f32_16x16x32_bf16 v[8:11], v[176:179], v[210:213], v[8:11]
	v_mfma_f32_16x16x32_bf16 v[4:7], v[168:171], v[218:221], v[4:7]
	v_mfma_f32_16x16x32_bf16 v[0:3], v[176:179], v[218:221], v[0:3]
	s_setprio 0
	s_barrier
	s_add_i32 s66, 0, 0x18000
	v_add_u32_e32 v155, s66, v151
	s_add_i32 s67, 0, 0x1c000
	ds_read_b128 v[142:145], v155
	ds_read_b128 v[146:149], v155 offset:1024
	ds_read_b128 v[156:159], v155 offset:2048
	ds_read_b128 v[160:163], v155 offset:3072
	v_add_u32_e32 v155, s67, v151
	ds_read_b128 v[164:167], v155
	ds_read_b128 v[168:171], v155 offset:1024
	ds_read_b128 v[172:175], v155 offset:2048
	ds_read_b128 v[176:179], v155 offset:3072
	s_add_u32 s44, s44, 0x80000
	s_addc_u32 s45, s45, 0
	s_mov_b32 m0, s48
	v_lshl_add_u64 v[230:231], s[44:45], 0, v[132:133]
	ds_read_b128 v[180:183], v154 offset:32768
	ds_read_b128 v[184:187], v154 offset:33792
	ds_read_b128 v[188:191], v154 offset:34816
	ds_read_b128 v[192:195], v154 offset:35840
	ds_read_b128 v[196:199], v154 offset:36864
	ds_read_b128 v[210:213], v154 offset:37888
	ds_read_b128 v[214:217], v154 offset:38912
	ds_read_b128 v[218:221], v154 offset:39936
	global_load_lds_dwordx4 v[230:231], off
	v_lshl_add_u64 v[230:231], s[44:45], 0, v[130:131]
	s_mov_b32 m0, s49
	s_nop 0
	global_load_lds_dwordx4 v[230:231], off
	s_waitcnt vmcnt(8)
	s_waitcnt lgkmcnt(0)
	s_barrier
	s_setprio 1
	v_mfma_f32_16x16x32_bf16 v[124:127], v[142:145], v[180:183], v[124:127]
	v_mfma_f32_16x16x32_bf16 v[120:123], v[156:159], v[180:183], v[120:123]
	v_mfma_f32_16x16x32_bf16 v[116:119], v[142:145], v[188:191], v[116:119]
	v_mfma_f32_16x16x32_bf16 v[112:115], v[156:159], v[188:191], v[112:115]
	v_mfma_f32_16x16x32_bf16 v[108:111], v[142:145], v[196:199], v[108:111]
	v_mfma_f32_16x16x32_bf16 v[104:107], v[156:159], v[196:199], v[104:107]
	v_mfma_f32_16x16x32_bf16 v[100:103], v[142:145], v[214:217], v[100:103]
	v_mfma_f32_16x16x32_bf16 v[96:99], v[156:159], v[214:217], v[96:99]
	v_mfma_f32_16x16x32_bf16 v[124:127], v[146:149], v[184:187], v[124:127]
	v_mfma_f32_16x16x32_bf16 v[120:123], v[160:163], v[184:187], v[120:123]
	v_mfma_f32_16x16x32_bf16 v[116:119], v[146:149], v[192:195], v[116:119]
	v_mfma_f32_16x16x32_bf16 v[112:115], v[160:163], v[192:195], v[112:115]
	v_mfma_f32_16x16x32_bf16 v[108:111], v[146:149], v[210:213], v[108:111]
	v_mfma_f32_16x16x32_bf16 v[104:107], v[160:163], v[210:213], v[104:107]
	v_mfma_f32_16x16x32_bf16 v[100:103], v[146:149], v[218:221], v[100:103]
	v_mfma_f32_16x16x32_bf16 v[96:99], v[160:163], v[218:221], v[96:99]
	v_mfma_f32_16x16x32_bf16 v[92:95], v[164:167], v[180:183], v[92:95]
	v_mfma_f32_16x16x32_bf16 v[88:91], v[172:175], v[180:183], v[88:91]
	v_mfma_f32_16x16x32_bf16 v[84:87], v[164:167], v[188:191], v[84:87]
	v_mfma_f32_16x16x32_bf16 v[80:83], v[172:175], v[188:191], v[80:83]
	v_mfma_f32_16x16x32_bf16 v[76:79], v[164:167], v[196:199], v[76:79]
	v_mfma_f32_16x16x32_bf16 v[72:75], v[172:175], v[196:199], v[72:75]
	v_mfma_f32_16x16x32_bf16 v[68:71], v[164:167], v[214:217], v[68:71]
	v_mfma_f32_16x16x32_bf16 v[64:67], v[172:175], v[214:217], v[64:67]
	v_mfma_f32_16x16x32_bf16 v[92:95], v[168:171], v[184:187], v[92:95]
	v_mfma_f32_16x16x32_bf16 v[88:91], v[176:179], v[184:187], v[88:91]
	v_mfma_f32_16x16x32_bf16 v[84:87], v[168:171], v[192:195], v[84:87]
	v_mfma_f32_16x16x32_bf16 v[80:83], v[176:179], v[192:195], v[80:83]
	v_mfma_f32_16x16x32_bf16 v[76:79], v[168:171], v[210:213], v[76:79]
	v_mfma_f32_16x16x32_bf16 v[72:75], v[176:179], v[210:213], v[72:75]
	v_mfma_f32_16x16x32_bf16 v[68:71], v[168:171], v[218:221], v[68:71]
	v_mfma_f32_16x16x32_bf16 v[64:67], v[176:179], v[218:221], v[64:67]
	s_setprio 0
	s_barrier
	s_add_i32 s44, s66, s2
	v_lshl_add_u64 v[222:223], v[222:223], 0, s[12:13]
	s_mov_b32 m0, s44
	ds_read_b128 v[180:183], v154 offset:49152
	ds_read_b128 v[184:187], v154 offset:50176
	ds_read_b128 v[188:191], v154 offset:51200
	ds_read_b128 v[192:195], v154 offset:52224
	ds_read_b128 v[196:199], v154 offset:53248
	ds_read_b128 v[210:213], v154 offset:54272
	ds_read_b128 v[214:217], v154 offset:55296
	ds_read_b128 v[218:221], v154 offset:56320
	global_load_lds_dwordx4 v[222:223], off
	s_add_i32 m0, s44, 0x2000
	s_add_u32 s42, s42, 0x80080
	v_lshl_add_u64 v[222:223], v[224:225], 0, s[12:13]
	s_addc_u32 s43, s43, 0
	s_add_i32 s44, s67, s2
	global_load_lds_dwordx4 v[222:223], off
	v_lshl_add_u64 v[222:223], s[42:43], 0, v[204:205]
	s_mov_b32 m0, s44
	s_nop 0
	global_load_lds_dwordx4 v[222:223], off
	v_lshl_add_u64 v[222:223], s[42:43], 0, v[128:129]
	s_add_i32 m0, s44, 0x2000
	s_nop 0
	global_load_lds_dwordx4 v[222:223], off
	v_lshl_add_u64 v[222:223], v[226:227], 0, s[12:13]
	s_mov_b32 m0, s50
	s_nop 0
	global_load_lds_dwordx4 v[222:223], off
	v_lshl_add_u64 v[222:223], v[228:229], 0, s[12:13]
	s_mov_b32 m0, s51
	s_nop 0
	global_load_lds_dwordx4 v[222:223], off
	s_waitcnt vmcnt(8)
	s_waitcnt lgkmcnt(0)
	s_barrier
	s_setprio 1
	v_mfma_f32_16x16x32_bf16 v[60:63], v[142:145], v[180:183], v[60:63]
	v_mfma_f32_16x16x32_bf16 v[56:59], v[156:159], v[180:183], v[56:59]
	v_mfma_f32_16x16x32_bf16 v[52:55], v[142:145], v[188:191], v[52:55]
	v_mfma_f32_16x16x32_bf16 v[48:51], v[156:159], v[188:191], v[48:51]
	v_mfma_f32_16x16x32_bf16 v[44:47], v[142:145], v[196:199], v[44:47]
	v_mfma_f32_16x16x32_bf16 v[40:43], v[156:159], v[196:199], v[40:43]
	v_mfma_f32_16x16x32_bf16 v[36:39], v[142:145], v[214:217], v[36:39]
	v_mfma_f32_16x16x32_bf16 v[32:35], v[156:159], v[214:217], v[32:35]
	v_mfma_f32_16x16x32_bf16 v[60:63], v[146:149], v[184:187], v[60:63]
	v_mfma_f32_16x16x32_bf16 v[56:59], v[160:163], v[184:187], v[56:59]
	v_mfma_f32_16x16x32_bf16 v[52:55], v[146:149], v[192:195], v[52:55]
	v_mfma_f32_16x16x32_bf16 v[48:51], v[160:163], v[192:195], v[48:51]
	v_mfma_f32_16x16x32_bf16 v[44:47], v[146:149], v[210:213], v[44:47]
	v_mfma_f32_16x16x32_bf16 v[40:43], v[160:163], v[210:213], v[40:43]
	v_mfma_f32_16x16x32_bf16 v[36:39], v[146:149], v[218:221], v[36:39]
	v_mfma_f32_16x16x32_bf16 v[32:35], v[160:163], v[218:221], v[32:35]
	v_mfma_f32_16x16x32_bf16 v[28:31], v[164:167], v[180:183], v[28:31]
	v_mfma_f32_16x16x32_bf16 v[24:27], v[172:175], v[180:183], v[24:27]
	v_mfma_f32_16x16x32_bf16 v[20:23], v[164:167], v[188:191], v[20:23]
	v_mfma_f32_16x16x32_bf16 v[16:19], v[172:175], v[188:191], v[16:19]
	v_mfma_f32_16x16x32_bf16 v[12:15], v[164:167], v[196:199], v[12:15]
	v_mfma_f32_16x16x32_bf16 v[8:11], v[172:175], v[196:199], v[8:11]
	v_mfma_f32_16x16x32_bf16 v[4:7], v[164:167], v[214:217], v[4:7]
	v_mfma_f32_16x16x32_bf16 v[0:3], v[172:175], v[214:217], v[0:3]
	v_mfma_f32_16x16x32_bf16 v[28:31], v[168:171], v[184:187], v[28:31]
	v_mfma_f32_16x16x32_bf16 v[24:27], v[176:179], v[184:187], v[24:27]
	v_mfma_f32_16x16x32_bf16 v[20:23], v[168:171], v[192:195], v[20:23]
	v_mfma_f32_16x16x32_bf16 v[16:19], v[176:179], v[192:195], v[16:19]
	v_mfma_f32_16x16x32_bf16 v[12:15], v[168:171], v[210:213], v[12:15]
	v_mfma_f32_16x16x32_bf16 v[8:11], v[176:179], v[210:213], v[8:11]
	v_mfma_f32_16x16x32_bf16 v[4:7], v[168:171], v[218:221], v[4:7]
	v_mfma_f32_16x16x32_bf16 v[0:3], v[176:179], v[218:221], v[0:3]
	s_setprio 0
	s_barrier
	s_add_i32 s65, s65, 2
	s_add_u32 s0, s0, 0x100
	s_addc_u32 s1, s1, 0
	s_cmp_gt_u32 s65, 29
	s_cbranch_scc1 .Lpeel_exit_114
.LBB0_114:
	s_add_u32 s42, s4, s0
	s_addc_u32 s43, s5, s1
	s_add_u32 s42, s42, 0x100
	s_addc_u32 s43, s43, 0
	s_add_u32 s66, s20, s0
	s_addc_u32 s67, s21, s1
	s_add_i32 s70, 0, 0x10000
	s_cmpk_eq_i32 s0, 0xf00
	s_cselect_b32 s45, s25, s43
	s_cselect_b32 s44, s37, s42
	v_add_u32_e32 v155, s70, v151
	s_cselect_b32 s43, s29, s67
	s_cselect_b32 s42, s64, s66
	s_add_i32 s71, 0, 0x14000
	ds_read_b128 v[142:145], v155
	ds_read_b128 v[146:149], v155 offset:1024
	ds_read_b128 v[156:159], v155 offset:2048
	ds_read_b128 v[160:163], v155 offset:3072
	v_add_u32_e32 v155, s71, v151
	ds_read_b128 v[164:167], v155
	ds_read_b128 v[168:171], v155 offset:1024
	ds_read_b128 v[172:175], v155 offset:2048
	ds_read_b128 v[176:179], v155 offset:3072
	v_lshl_add_u64 v[222:223], v[138:139], 0, s[0:1]
	s_add_i32 m0, s46, 0xc000
	ds_read_b128 v[180:183], v154
	ds_read_b128 v[184:187], v154 offset:1024
	ds_read_b128 v[188:191], v154 offset:2048
	ds_read_b128 v[192:195], v154 offset:3072
	ds_read_b128 v[196:199], v154 offset:4096
	ds_read_b128 v[210:213], v154 offset:5120
	ds_read_b128 v[214:217], v154 offset:6144
	ds_read_b128 v[218:221], v154 offset:7168
	global_load_lds_dwordx4 v[222:223], off
	v_lshl_add_u64 v[222:223], v[140:141], 0, s[0:1]
	s_add_i32 m0, s46, 0xe000
	s_nop 0
	global_load_lds_dwordx4 v[222:223], off
	s_waitcnt vmcnt(8)
	s_waitcnt lgkmcnt(0)
	s_barrier
	s_setprio 1
	v_mfma_f32_16x16x32_bf16 v[124:127], v[142:145], v[180:183], v[124:127]
	v_mfma_f32_16x16x32_bf16 v[120:123], v[156:159], v[180:183], v[120:123]
	v_mfma_f32_16x16x32_bf16 v[116:119], v[142:145], v[188:191], v[116:119]
	v_mfma_f32_16x16x32_bf16 v[112:115], v[156:159], v[188:191], v[112:115]
	v_mfma_f32_16x16x32_bf16 v[108:111], v[142:145], v[196:199], v[108:111]
	v_mfma_f32_16x16x32_bf16 v[104:107], v[156:159], v[196:199], v[104:107]
	v_mfma_f32_16x16x32_bf16 v[100:103], v[142:145], v[214:217], v[100:103]
	v_mfma_f32_16x16x32_bf16 v[96:99], v[156:159], v[214:217], v[96:99]
	v_mfma_f32_16x16x32_bf16 v[124:127], v[146:149], v[184:187], v[124:127]
	v_mfma_f32_16x16x32_bf16 v[120:123], v[160:163], v[184:187], v[120:123]
	v_mfma_f32_16x16x32_bf16 v[116:119], v[146:149], v[192:195], v[116:119]
	v_mfma_f32_16x16x32_bf16 v[112:115], v[160:163], v[192:195], v[112:115]
	v_mfma_f32_16x16x32_bf16 v[108:111], v[146:149], v[210:213], v[108:111]
	v_mfma_f32_16x16x32_bf16 v[104:107], v[160:163], v[210:213], v[104:107]
	v_mfma_f32_16x16x32_bf16 v[100:103], v[146:149], v[218:221], v[100:103]
	v_mfma_f32_16x16x32_bf16 v[96:99], v[160:163], v[218:221], v[96:99]
	v_mfma_f32_16x16x32_bf16 v[92:95], v[164:167], v[180:183], v[92:95]
	v_mfma_f32_16x16x32_bf16 v[88:91], v[172:175], v[180:183], v[88:91]
	v_mfma_f32_16x16x32_bf16 v[84:87], v[164:167], v[188:191], v[84:87]
	v_mfma_f32_16x16x32_bf16 v[80:83], v[172:175], v[188:191], v[80:83]
	v_mfma_f32_16x16x32_bf16 v[76:79], v[164:167], v[196:199], v[76:79]
	v_mfma_f32_16x16x32_bf16 v[72:75], v[172:175], v[196:199], v[72:75]
	v_mfma_f32_16x16x32_bf16 v[68:71], v[164:167], v[214:217], v[68:71]
	v_mfma_f32_16x16x32_bf16 v[64:67], v[172:175], v[214:217], v[64:67]
	v_mfma_f32_16x16x32_bf16 v[92:95], v[168:171], v[184:187], v[92:95]
	v_mfma_f32_16x16x32_bf16 v[88:91], v[176:179], v[184:187], v[88:91]
	v_mfma_f32_16x16x32_bf16 v[84:87], v[168:171], v[192:195], v[84:87]
	v_mfma_f32_16x16x32_bf16 v[80:83], v[176:179], v[192:195], v[80:83]
	v_mfma_f32_16x16x32_bf16 v[76:79], v[168:171], v[210:213], v[76:79]
	v_mfma_f32_16x16x32_bf16 v[72:75], v[176:179], v[210:213], v[72:75]
	v_mfma_f32_16x16x32_bf16 v[68:71], v[168:171], v[218:221], v[68:71]
	v_mfma_f32_16x16x32_bf16 v[64:67], v[176:179], v[218:221], v[64:67]
	s_setprio 0
	s_barrier
	s_add_i32 s66, s70, s2
	v_lshl_add_u64 v[222:223], s[42:43], 0, v[204:205]
	s_mov_b32 m0, s66
	ds_read_b128 v[180:183], v154 offset:16384
	ds_read_b128 v[184:187], v154 offset:17408
	ds_read_b128 v[188:191], v154 offset:18432
	ds_read_b128 v[192:195], v154 offset:19456
	ds_read_b128 v[196:199], v154 offset:20480
	ds_read_b128 v[210:213], v154 offset:21504
	ds_read_b128 v[214:217], v154 offset:22528
	ds_read_b128 v[218:221], v154 offset:23552
	global_load_lds_dwordx4 v[222:223], off
	s_add_i32 m0, s66, 0x2000
	s_add_u32 s66, s42, 0x80000
	v_lshl_add_u64 v[224:225], s[42:43], 0, v[128:129]
	s_addc_u32 s67, s43, 0
	s_add_i32 s70, s71, s2
	global_load_lds_dwordx4 v[224:225], off
	v_lshl_add_u64 v[226:227], s[66:67], 0, v[204:205]
	s_mov_b32 m0, s70
	v_lshl_add_u64 v[228:229], s[44:45], 0, v[130:131]
	global_load_lds_dwordx4 v[226:227], off
	v_lshl_add_u64 v[226:227], s[66:67], 0, v[128:129]
	s_add_i32 m0, s70, 0x2000
	s_nop 0
	global_load_lds_dwordx4 v[226:227], off
	v_lshl_add_u64 v[226:227], s[44:45], 0, v[132:133]
	s_mov_b32 m0, s46
	s_nop 0
	global_load_lds_dwordx4 v[226:227], off
	s_mov_b32 m0, s47
	s_nop 0
	global_load_lds_dwordx4 v[228:229], off
	s_waitcnt vmcnt(8)
	s_waitcnt lgkmcnt(0)
	s_barrier
	s_setprio 1
	v_mfma_f32_16x16x32_bf16 v[60:63], v[142:145], v[180:183], v[60:63]
	v_mfma_f32_16x16x32_bf16 v[56:59], v[156:159], v[180:183], v[56:59]
	v_mfma_f32_16x16x32_bf16 v[52:55], v[142:145], v[188:191], v[52:55]
	v_mfma_f32_16x16x32_bf16 v[48:51], v[156:159], v[188:191], v[48:51]
	v_mfma_f32_16x16x32_bf16 v[44:47], v[142:145], v[196:199], v[44:47]
	v_mfma_f32_16x16x32_bf16 v[40:43], v[156:159], v[196:199], v[40:43]
	v_mfma_f32_16x16x32_bf16 v[36:39], v[142:145], v[214:217], v[36:39]
	v_mfma_f32_16x16x32_bf16 v[32:35], v[156:159], v[214:217], v[32:35]
	v_mfma_f32_16x16x32_bf16 v[60:63], v[146:149], v[184:187], v[60:63]
	v_mfma_f32_16x16x32_bf16 v[56:59], v[160:163], v[184:187], v[56:59]
	v_mfma_f32_16x16x32_bf16 v[52:55], v[146:149], v[192:195], v[52:55]
	v_mfma_f32_16x16x32_bf16 v[48:51], v[160:163], v[192:195], v[48:51]
	v_mfma_f32_16x16x32_bf16 v[44:47], v[146:149], v[210:213], v[44:47]
	v_mfma_f32_16x16x32_bf16 v[40:43], v[160:163], v[210:213], v[40:43]
	v_mfma_f32_16x16x32_bf16 v[36:39], v[146:149], v[218:221], v[36:39]
	v_mfma_f32_16x16x32_bf16 v[32:35], v[160:163], v[218:221], v[32:35]
	v_mfma_f32_16x16x32_bf16 v[28:31], v[164:167], v[180:183], v[28:31]
	v_mfma_f32_16x16x32_bf16 v[24:27], v[172:175], v[180:183], v[24:27]
	v_mfma_f32_16x16x32_bf16 v[20:23], v[164:167], v[188:191], v[20:23]
	v_mfma_f32_16x16x32_bf16 v[16:19], v[172:175], v[188:191], v[16:19]
	v_mfma_f32_16x16x32_bf16 v[12:15], v[164:167], v[196:199], v[12:15]
	v_mfma_f32_16x16x32_bf16 v[8:11], v[172:175], v[196:199], v[8:11]
	v_mfma_f32_16x16x32_bf16 v[4:7], v[164:167], v[214:217], v[4:7]
	v_mfma_f32_16x16x32_bf16 v[0:3], v[172:175], v[214:217], v[0:3]
	v_mfma_f32_16x16x32_bf16 v[28:31], v[168:171], v[184:187], v[28:31]
	v_mfma_f32_16x16x32_bf16 v[24:27], v[176:179], v[184:187], v[24:27]
	v_mfma_f32_16x16x32_bf16 v[20:23], v[168:171], v[192:195], v[20:23]
	v_mfma_f32_16x16x32_bf16 v[16:19], v[176:179], v[192:195], v[16:19]
	v_mfma_f32_16x16x32_bf16 v[12:15], v[168:171], v[210:213], v[12:15]
	v_mfma_f32_16x16x32_bf16 v[8:11], v[176:179], v[210:213], v[8:11]
	v_mfma_f32_16x16x32_bf16 v[4:7], v[168:171], v[218:221], v[4:7]
	v_mfma_f32_16x16x32_bf16 v[0:3], v[176:179], v[218:221], v[0:3]
	s_setprio 0
	s_barrier
	s_add_i32 s66, 0, 0x18000
	v_add_u32_e32 v155, s66, v151
	s_add_i32 s67, 0, 0x1c000
	ds_read_b128 v[142:145], v155
	ds_read_b128 v[146:149], v155 offset:1024
	ds_read_b128 v[156:159], v155 offset:2048
	ds_read_b128 v[160:163], v155 offset:3072
	v_add_u32_e32 v155, s67, v151
	ds_read_b128 v[164:167], v155
	ds_read_b128 v[168:171], v155 offset:1024
	ds_read_b128 v[172:175], v155 offset:2048
	ds_read_b128 v[176:179], v155 offset:3072
	s_add_u32 s44, s44, 0x80000
	s_addc_u32 s45, s45, 0
	s_mov_b32 m0, s48
	v_lshl_add_u64 v[230:231], s[44:45], 0, v[132:133]
	ds_read_b128 v[180:183], v154 offset:32768
	ds_read_b128 v[184:187], v154 offset:33792
	ds_read_b128 v[188:191], v154 offset:34816
	ds_read_b128 v[192:195], v154 offset:35840
	ds_read_b128 v[196:199], v154 offset:36864
	ds_read_b128 v[210:213], v154 offset:37888
	ds_read_b128 v[214:217], v154 offset:38912
	ds_read_b128 v[218:221], v154 offset:39936
	global_load_lds_dwordx4 v[230:231], off
	v_lshl_add_u64 v[230:231], s[44:45], 0, v[130:131]
	s_mov_b32 m0, s49
	s_nop 0
	global_load_lds_dwordx4 v[230:231], off
	s_waitcnt vmcnt(8)
	s_waitcnt lgkmcnt(0)
	s_barrier
	s_setprio 1
	v_mfma_f32_16x16x32_bf16 v[124:127], v[142:145], v[180:183], v[124:127]
	v_mfma_f32_16x16x32_bf16 v[120:123], v[156:159], v[180:183], v[120:123]
	v_mfma_f32_16x16x32_bf16 v[116:119], v[142:145], v[188:191], v[116:119]
	v_mfma_f32_16x16x32_bf16 v[112:115], v[156:159], v[188:191], v[112:115]
	v_mfma_f32_16x16x32_bf16 v[108:111], v[142:145], v[196:199], v[108:111]
	v_mfma_f32_16x16x32_bf16 v[104:107], v[156:159], v[196:199], v[104:107]
	v_mfma_f32_16x16x32_bf16 v[100:103], v[142:145], v[214:217], v[100:103]
	v_mfma_f32_16x16x32_bf16 v[96:99], v[156:159], v[214:217], v[96:99]
	v_mfma_f32_16x16x32_bf16 v[124:127], v[146:149], v[184:187], v[124:127]
	v_mfma_f32_16x16x32_bf16 v[120:123], v[160:163], v[184:187], v[120:123]
	v_mfma_f32_16x16x32_bf16 v[116:119], v[146:149], v[192:195], v[116:119]
	v_mfma_f32_16x16x32_bf16 v[112:115], v[160:163], v[192:195], v[112:115]
	v_mfma_f32_16x16x32_bf16 v[108:111], v[146:149], v[210:213], v[108:111]
	v_mfma_f32_16x16x32_bf16 v[104:107], v[160:163], v[210:213], v[104:107]
	v_mfma_f32_16x16x32_bf16 v[100:103], v[146:149], v[218:221], v[100:103]
	v_mfma_f32_16x16x32_bf16 v[96:99], v[160:163], v[218:221], v[96:99]
	v_mfma_f32_16x16x32_bf16 v[92:95], v[164:167], v[180:183], v[92:95]
	v_mfma_f32_16x16x32_bf16 v[88:91], v[172:175], v[180:183], v[88:91]
	v_mfma_f32_16x16x32_bf16 v[84:87], v[164:167], v[188:191], v[84:87]
	v_mfma_f32_16x16x32_bf16 v[80:83], v[172:175], v[188:191], v[80:83]
	v_mfma_f32_16x16x32_bf16 v[76:79], v[164:167], v[196:199], v[76:79]
	v_mfma_f32_16x16x32_bf16 v[72:75], v[172:175], v[196:199], v[72:75]
	v_mfma_f32_16x16x32_bf16 v[68:71], v[164:167], v[214:217], v[68:71]
	v_mfma_f32_16x16x32_bf16 v[64:67], v[172:175], v[214:217], v[64:67]
	v_mfma_f32_16x16x32_bf16 v[92:95], v[168:171], v[184:187], v[92:95]
	v_mfma_f32_16x16x32_bf16 v[88:91], v[176:179], v[184:187], v[88:91]
	v_mfma_f32_16x16x32_bf16 v[84:87], v[168:171], v[192:195], v[84:87]
	v_mfma_f32_16x16x32_bf16 v[80:83], v[176:179], v[192:195], v[80:83]
	v_mfma_f32_16x16x32_bf16 v[76:79], v[168:171], v[210:213], v[76:79]
	v_mfma_f32_16x16x32_bf16 v[72:75], v[176:179], v[210:213], v[72:75]
	v_mfma_f32_16x16x32_bf16 v[68:71], v[168:171], v[218:221], v[68:71]
	v_mfma_f32_16x16x32_bf16 v[64:67], v[176:179], v[218:221], v[64:67]
	s_setprio 0
	s_barrier
	s_add_i32 s44, s66, s2
	v_lshl_add_u64 v[222:223], v[222:223], 0, s[12:13]
	s_mov_b32 m0, s44
	ds_read_b128 v[180:183], v154 offset:49152
	ds_read_b128 v[184:187], v154 offset:50176
	ds_read_b128 v[188:191], v154 offset:51200
	ds_read_b128 v[192:195], v154 offset:52224
	ds_read_b128 v[196:199], v154 offset:53248
	ds_read_b128 v[210:213], v154 offset:54272
	ds_read_b128 v[214:217], v154 offset:55296
	ds_read_b128 v[218:221], v154 offset:56320
	global_load_lds_dwordx4 v[222:223], off
	s_add_i32 m0, s44, 0x2000
	s_add_u32 s42, s42, 0x80080
	v_lshl_add_u64 v[222:223], v[224:225], 0, s[12:13]
	s_addc_u32 s43, s43, 0
	s_add_i32 s44, s67, s2
	global_load_lds_dwordx4 v[222:223], off
	v_lshl_add_u64 v[222:223], s[42:43], 0, v[204:205]
	s_mov_b32 m0, s44
	s_nop 0
	global_load_lds_dwordx4 v[222:223], off
	v_lshl_add_u64 v[222:223], s[42:43], 0, v[128:129]
	s_add_i32 m0, s44, 0x2000
	s_nop 0
	global_load_lds_dwordx4 v[222:223], off
	v_lshl_add_u64 v[222:223], v[226:227], 0, s[12:13]
	s_mov_b32 m0, s50
	s_nop 0
	global_load_lds_dwordx4 v[222:223], off
	v_lshl_add_u64 v[222:223], v[228:229], 0, s[12:13]
	s_mov_b32 m0, s51
	s_nop 0
	global_load_lds_dwordx4 v[222:223], off
	s_waitcnt vmcnt(8)
	s_waitcnt lgkmcnt(0)
	s_barrier
	s_setprio 1
	v_mfma_f32_16x16x32_bf16 v[60:63], v[142:145], v[180:183], v[60:63]
	v_mfma_f32_16x16x32_bf16 v[56:59], v[156:159], v[180:183], v[56:59]
	v_mfma_f32_16x16x32_bf16 v[52:55], v[142:145], v[188:191], v[52:55]
	v_mfma_f32_16x16x32_bf16 v[48:51], v[156:159], v[188:191], v[48:51]
	v_mfma_f32_16x16x32_bf16 v[44:47], v[142:145], v[196:199], v[44:47]
	v_mfma_f32_16x16x32_bf16 v[40:43], v[156:159], v[196:199], v[40:43]
	v_mfma_f32_16x16x32_bf16 v[36:39], v[142:145], v[214:217], v[36:39]
	v_mfma_f32_16x16x32_bf16 v[32:35], v[156:159], v[214:217], v[32:35]
	v_mfma_f32_16x16x32_bf16 v[60:63], v[146:149], v[184:187], v[60:63]
	v_mfma_f32_16x16x32_bf16 v[56:59], v[160:163], v[184:187], v[56:59]
	v_mfma_f32_16x16x32_bf16 v[52:55], v[146:149], v[192:195], v[52:55]
	v_mfma_f32_16x16x32_bf16 v[48:51], v[160:163], v[192:195], v[48:51]
	v_mfma_f32_16x16x32_bf16 v[44:47], v[146:149], v[210:213], v[44:47]
	v_mfma_f32_16x16x32_bf16 v[40:43], v[160:163], v[210:213], v[40:43]
	v_mfma_f32_16x16x32_bf16 v[36:39], v[146:149], v[218:221], v[36:39]
	v_mfma_f32_16x16x32_bf16 v[32:35], v[160:163], v[218:221], v[32:35]
	v_mfma_f32_16x16x32_bf16 v[28:31], v[164:167], v[180:183], v[28:31]
	v_mfma_f32_16x16x32_bf16 v[24:27], v[172:175], v[180:183], v[24:27]
	v_mfma_f32_16x16x32_bf16 v[20:23], v[164:167], v[188:191], v[20:23]
	v_mfma_f32_16x16x32_bf16 v[16:19], v[172:175], v[188:191], v[16:19]
	v_mfma_f32_16x16x32_bf16 v[12:15], v[164:167], v[196:199], v[12:15]
	v_mfma_f32_16x16x32_bf16 v[8:11], v[172:175], v[196:199], v[8:11]
	v_mfma_f32_16x16x32_bf16 v[4:7], v[164:167], v[214:217], v[4:7]
	v_mfma_f32_16x16x32_bf16 v[0:3], v[172:175], v[214:217], v[0:3]
	v_mfma_f32_16x16x32_bf16 v[28:31], v[168:171], v[184:187], v[28:31]
	v_mfma_f32_16x16x32_bf16 v[24:27], v[176:179], v[184:187], v[24:27]
	v_mfma_f32_16x16x32_bf16 v[20:23], v[168:171], v[192:195], v[20:23]
	v_mfma_f32_16x16x32_bf16 v[16:19], v[176:179], v[192:195], v[16:19]
	v_mfma_f32_16x16x32_bf16 v[12:15], v[168:171], v[210:213], v[12:15]
	v_mfma_f32_16x16x32_bf16 v[8:11], v[176:179], v[210:213], v[8:11]
	v_mfma_f32_16x16x32_bf16 v[4:7], v[168:171], v[218:221], v[4:7]
	v_mfma_f32_16x16x32_bf16 v[0:3], v[176:179], v[218:221], v[0:3]
	s_setprio 0
	s_barrier
	s_add_i32 s65, s65, 2
	s_add_u32 s0, s0, 0x100
	s_addc_u32 s1, s1, 0
	s_cmp_gt_u32 s65, 29
	s_cbranch_scc0 .LBB0_114

.LBB0_182:
	s_add_u32 s0, s0, 0x80
	s_addc_u32 s1, s1, 0
	s_add_u32 s21, s36, 0x100
	s_addc_u32 s22, s37, 0
	s_mov_b32 s4, 0
	s_add_i32 s25, s4, 2
	s_add_u32 s28, s0, 0x80
	s_addc_u32 s5, s1, 0
	s_add_i32 s36, 0, 0x10000
	s_cmp_eq_u32 s63, s4
	s_cselect_b32 s5, s49, s5
	s_cselect_b32 s4, s48, s28
	s_cselect_b32 s29, s51, s22
	s_cselect_b32 s28, s50, s21
	s_add_i32 s37, 0, 0x14000
	v_add_u32_e32 v100, s36, v249
	v_add_u32_e32 v156, s37, v249
	ds_read_b128 v[88:91], v100
	ds_read_b128 v[92:95], v100 offset:1024
	ds_read_b128 v[96:99], v100 offset:2048
	ds_read_b128 v[100:103], v100 offset:3072
	s_waitcnt lgkmcnt(0)
	ds_read_b128 v[144:147], v156
	ds_read_b128 v[148:151], v156 offset:1024
	ds_read_b128 v[152:155], v156 offset:2048
	ds_read_b128 v[156:159], v156 offset:3072
	v_lshl_add_u64 v[192:193], s[0:1], 0, v[216:217]
	s_add_i32 m0, s3, 0xc000
	ds_read_b128 v[160:163], v251
	ds_read_b128 v[164:167], v251 offset:1024
	ds_read_b128 v[168:171], v251 offset:2048
	ds_read_b128 v[172:175], v251 offset:3072
	ds_read_b128 v[176:179], v251 offset:4096
	ds_read_b128 v[180:183], v251 offset:5120
	ds_read_b128 v[184:187], v251 offset:6144
	ds_read_b128 v[188:191], v251 offset:7168
	global_load_lds_dwordx4 v[192:193], off
	v_lshl_add_u64 v[192:193], s[0:1], 0, v[218:219]
	s_add_i32 m0, s3, 0xe000
	s_nop 0
	global_load_lds_dwordx4 v[192:193], off
	s_waitcnt vmcnt(8)
	s_waitcnt lgkmcnt(0)
	s_barrier
	s_setprio 1
	v_mfma_f32_16x16x32_bf16 v[140:143], v[88:91], v[160:163], 0
	v_mfma_f32_16x16x32_bf16 v[136:139], v[96:99], v[160:163], 0
	v_mfma_f32_16x16x32_bf16 v[124:127], v[88:91], v[168:171], 0
	v_mfma_f32_16x16x32_bf16 v[120:123], v[96:99], v[168:171], 0
	v_mfma_f32_16x16x32_bf16 v[108:111], v[88:91], v[176:179], 0
	v_mfma_f32_16x16x32_bf16 v[104:107], v[96:99], v[176:179], 0
	v_mfma_f32_16x16x32_bf16 v[76:79], v[88:91], v[184:187], 0
	v_mfma_f32_16x16x32_bf16 v[72:75], v[96:99], v[184:187], 0
	v_mfma_f32_16x16x32_bf16 v[140:143], v[92:95], v[164:167], v[140:143]
	v_mfma_f32_16x16x32_bf16 v[136:139], v[100:103], v[164:167], v[136:139]
	v_mfma_f32_16x16x32_bf16 v[124:127], v[92:95], v[172:175], v[124:127]
	v_mfma_f32_16x16x32_bf16 v[120:123], v[100:103], v[172:175], v[120:123]
	v_mfma_f32_16x16x32_bf16 v[108:111], v[92:95], v[180:183], v[108:111]
	v_mfma_f32_16x16x32_bf16 v[104:107], v[100:103], v[180:183], v[104:107]
	v_mfma_f32_16x16x32_bf16 v[76:79], v[92:95], v[188:191], v[76:79]
	v_mfma_f32_16x16x32_bf16 v[72:75], v[100:103], v[188:191], v[72:75]
	v_mfma_f32_16x16x32_bf16 v[132:135], v[144:147], v[160:163], 0
	v_mfma_f32_16x16x32_bf16 v[128:131], v[152:155], v[160:163], 0
	v_mfma_f32_16x16x32_bf16 v[116:119], v[144:147], v[168:171], 0
	v_mfma_f32_16x16x32_bf16 v[112:115], v[152:155], v[168:171], 0
	v_mfma_f32_16x16x32_bf16 v[84:87], v[144:147], v[176:179], 0
	v_mfma_f32_16x16x32_bf16 v[80:83], v[152:155], v[176:179], 0
	v_mfma_f32_16x16x32_bf16 v[68:71], v[144:147], v[184:187], 0
	v_mfma_f32_16x16x32_bf16 v[64:67], v[152:155], v[184:187], 0
	v_mfma_f32_16x16x32_bf16 v[132:135], v[148:151], v[164:167], v[132:135]
	v_mfma_f32_16x16x32_bf16 v[128:131], v[156:159], v[164:167], v[128:131]
	v_mfma_f32_16x16x32_bf16 v[116:119], v[148:151], v[172:175], v[116:119]
	v_mfma_f32_16x16x32_bf16 v[112:115], v[156:159], v[172:175], v[112:115]
	v_mfma_f32_16x16x32_bf16 v[84:87], v[148:151], v[180:183], v[84:87]
	v_mfma_f32_16x16x32_bf16 v[80:83], v[156:159], v[180:183], v[80:83]
	v_mfma_f32_16x16x32_bf16 v[68:71], v[148:151], v[188:191], v[68:71]
	v_mfma_f32_16x16x32_bf16 v[64:67], v[156:159], v[188:191], v[64:67]
	s_setprio 0
	s_barrier
	s_add_i32 s36, s36, s2
	v_lshl_add_u64 v[192:193], s[28:29], 0, v[204:205]
	s_mov_b32 m0, s36
	ds_read_b128 v[160:163], v251 offset:16384
	ds_read_b128 v[164:167], v251 offset:17408
	ds_read_b128 v[168:171], v251 offset:18432
	ds_read_b128 v[172:175], v251 offset:19456
	ds_read_b128 v[176:179], v251 offset:20480
	ds_read_b128 v[180:183], v251 offset:21504
	ds_read_b128 v[184:187], v251 offset:22528
	ds_read_b128 v[188:191], v251 offset:23552
	global_load_lds_dwordx4 v[192:193], off
	s_add_i32 m0, s36, 0x2000
	v_lshl_add_u64 v[194:195], s[28:29], 0, v[210:211]
	s_add_u32 s28, s28, s10
	s_addc_u32 s29, s29, 0
	s_add_i32 s36, s37, s2
	global_load_lds_dwordx4 v[194:195], off
	v_lshl_add_u64 v[196:197], s[28:29], 0, v[204:205]
	s_mov_b32 m0, s36
	v_lshl_add_u64 v[198:199], s[28:29], 0, v[210:211]
	global_load_lds_dwordx4 v[196:197], off
	s_add_i32 m0, s36, 0x2000
	v_lshl_add_u64 v[220:221], s[4:5], 0, v[214:215]
	global_load_lds_dwordx4 v[198:199], off
	s_mov_b32 m0, s3
	v_lshl_add_u64 v[222:223], s[4:5], 0, v[212:213]
	global_load_lds_dwordx4 v[220:221], off
	s_mov_b32 m0, s52
	s_nop 0
	global_load_lds_dwordx4 v[222:223], off
	s_waitcnt vmcnt(8)
	s_waitcnt lgkmcnt(0)
	s_barrier
	s_setprio 1
	v_mfma_f32_16x16x32_bf16 v[60:63], v[88:91], v[160:163], 0
	v_mfma_f32_16x16x32_bf16 v[56:59], v[96:99], v[160:163], 0
	v_mfma_f32_16x16x32_bf16 v[44:47], v[88:91], v[168:171], 0
	v_mfma_f32_16x16x32_bf16 v[40:43], v[96:99], v[168:171], 0
	v_mfma_f32_16x16x32_bf16 v[28:31], v[88:91], v[176:179], 0
	v_mfma_f32_16x16x32_bf16 v[24:27], v[96:99], v[176:179], 0
	v_mfma_f32_16x16x32_bf16 v[12:15], v[88:91], v[184:187], 0
	v_mfma_f32_16x16x32_bf16 v[8:11], v[96:99], v[184:187], 0
	v_mfma_f32_16x16x32_bf16 v[60:63], v[92:95], v[164:167], v[60:63]
	v_mfma_f32_16x16x32_bf16 v[56:59], v[100:103], v[164:167], v[56:59]
	v_mfma_f32_16x16x32_bf16 v[44:47], v[92:95], v[172:175], v[44:47]
	v_mfma_f32_16x16x32_bf16 v[40:43], v[100:103], v[172:175], v[40:43]
	v_mfma_f32_16x16x32_bf16 v[28:31], v[92:95], v[180:183], v[28:31]
	v_mfma_f32_16x16x32_bf16 v[24:27], v[100:103], v[180:183], v[24:27]
	v_mfma_f32_16x16x32_bf16 v[12:15], v[92:95], v[188:191], v[12:15]
	v_mfma_f32_16x16x32_bf16 v[8:11], v[100:103], v[188:191], v[8:11]
	v_mfma_f32_16x16x32_bf16 v[52:55], v[144:147], v[160:163], 0
	v_mfma_f32_16x16x32_bf16 v[48:51], v[152:155], v[160:163], 0
	v_mfma_f32_16x16x32_bf16 v[36:39], v[144:147], v[168:171], 0
	v_mfma_f32_16x16x32_bf16 v[32:35], v[152:155], v[168:171], 0
	v_mfma_f32_16x16x32_bf16 v[20:23], v[144:147], v[176:179], 0
	v_mfma_f32_16x16x32_bf16 v[16:19], v[152:155], v[176:179], 0
	v_mfma_f32_16x16x32_bf16 v[4:7], v[144:147], v[184:187], 0
	v_mfma_f32_16x16x32_bf16 v[0:3], v[152:155], v[184:187], 0
	v_mfma_f32_16x16x32_bf16 v[52:55], v[148:151], v[164:167], v[52:55]
	v_mfma_f32_16x16x32_bf16 v[48:51], v[156:159], v[164:167], v[48:51]
	v_mfma_f32_16x16x32_bf16 v[36:39], v[148:151], v[172:175], v[36:39]
	v_mfma_f32_16x16x32_bf16 v[32:35], v[156:159], v[172:175], v[32:35]
	v_mfma_f32_16x16x32_bf16 v[20:23], v[148:151], v[180:183], v[20:23]
	v_mfma_f32_16x16x32_bf16 v[16:19], v[156:159], v[180:183], v[16:19]
	v_mfma_f32_16x16x32_bf16 v[4:7], v[148:151], v[188:191], v[4:7]
	v_mfma_f32_16x16x32_bf16 v[0:3], v[156:159], v[188:191], v[0:3]
	s_setprio 0
	s_barrier
	s_add_i32 s28, 0, 0x18000
	s_add_i32 s29, 0, 0x1c000
	v_add_u32_e32 v100, s28, v249
	v_add_u32_e32 v156, s29, v249
	ds_read_b128 v[88:91], v100
	ds_read_b128 v[92:95], v100 offset:1024
	ds_read_b128 v[96:99], v100 offset:2048
	ds_read_b128 v[100:103], v100 offset:3072
	ds_read_b128 v[144:147], v156
	ds_read_b128 v[148:151], v156 offset:1024
	ds_read_b128 v[152:155], v156 offset:2048
	ds_read_b128 v[156:159], v156 offset:3072
	s_add_u32 s4, s4, s10
	s_addc_u32 s5, s5, 0
	s_mov_b32 m0, s53
	v_lshl_add_u64 v[224:225], s[4:5], 0, v[214:215]
	ds_read_b128 v[160:163], v251 offset:32768
	ds_read_b128 v[164:167], v251 offset:33792
	ds_read_b128 v[168:171], v251 offset:34816
	ds_read_b128 v[172:175], v251 offset:35840
	ds_read_b128 v[176:179], v251 offset:36864
	ds_read_b128 v[180:183], v251 offset:37888
	ds_read_b128 v[184:187], v251 offset:38912
	ds_read_b128 v[188:191], v251 offset:39936
	global_load_lds_dwordx4 v[224:225], off
	v_lshl_add_u64 v[224:225], s[4:5], 0, v[212:213]
	s_mov_b32 m0, s54
	s_nop 0
	global_load_lds_dwordx4 v[224:225], off
	s_waitcnt vmcnt(8)
	s_waitcnt lgkmcnt(0)
	s_barrier
	s_setprio 1
	v_mfma_f32_16x16x32_bf16 v[140:143], v[88:91], v[160:163], v[140:143]
	v_mfma_f32_16x16x32_bf16 v[136:139], v[96:99], v[160:163], v[136:139]
	v_mfma_f32_16x16x32_bf16 v[124:127], v[88:91], v[168:171], v[124:127]
	v_mfma_f32_16x16x32_bf16 v[120:123], v[96:99], v[168:171], v[120:123]
	v_mfma_f32_16x16x32_bf16 v[108:111], v[88:91], v[176:179], v[108:111]
	v_mfma_f32_16x16x32_bf16 v[104:107], v[96:99], v[176:179], v[104:107]
	v_mfma_f32_16x16x32_bf16 v[76:79], v[88:91], v[184:187], v[76:79]
	v_mfma_f32_16x16x32_bf16 v[72:75], v[96:99], v[184:187], v[72:75]
	v_mfma_f32_16x16x32_bf16 v[140:143], v[92:95], v[164:167], v[140:143]
	v_mfma_f32_16x16x32_bf16 v[136:139], v[100:103], v[164:167], v[136:139]
	v_mfma_f32_16x16x32_bf16 v[124:127], v[92:95], v[172:175], v[124:127]
	v_mfma_f32_16x16x32_bf16 v[120:123], v[100:103], v[172:175], v[120:123]
	v_mfma_f32_16x16x32_bf16 v[108:111], v[92:95], v[180:183], v[108:111]
	v_mfma_f32_16x16x32_bf16 v[104:107], v[100:103], v[180:183], v[104:107]
	v_mfma_f32_16x16x32_bf16 v[76:79], v[92:95], v[188:191], v[76:79]
	v_mfma_f32_16x16x32_bf16 v[72:75], v[100:103], v[188:191], v[72:75]
	v_mfma_f32_16x16x32_bf16 v[132:135], v[144:147], v[160:163], v[132:135]
	v_mfma_f32_16x16x32_bf16 v[128:131], v[152:155], v[160:163], v[128:131]
	v_mfma_f32_16x16x32_bf16 v[116:119], v[144:147], v[168:171], v[116:119]
	v_mfma_f32_16x16x32_bf16 v[112:115], v[152:155], v[168:171], v[112:115]
	v_mfma_f32_16x16x32_bf16 v[84:87], v[144:147], v[176:179], v[84:87]
	v_mfma_f32_16x16x32_bf16 v[80:83], v[152:155], v[176:179], v[80:83]
	v_mfma_f32_16x16x32_bf16 v[68:71], v[144:147], v[184:187], v[68:71]
	v_mfma_f32_16x16x32_bf16 v[64:67], v[152:155], v[184:187], v[64:67]
	v_mfma_f32_16x16x32_bf16 v[132:135], v[148:151], v[164:167], v[132:135]
	v_mfma_f32_16x16x32_bf16 v[128:131], v[156:159], v[164:167], v[128:131]
	v_mfma_f32_16x16x32_bf16 v[116:119], v[148:151], v[172:175], v[116:119]
	v_mfma_f32_16x16x32_bf16 v[112:115], v[156:159], v[172:175], v[112:115]
	v_mfma_f32_16x16x32_bf16 v[84:87], v[148:151], v[180:183], v[84:87]
	v_mfma_f32_16x16x32_bf16 v[80:83], v[156:159], v[180:183], v[80:83]
	v_mfma_f32_16x16x32_bf16 v[68:71], v[148:151], v[188:191], v[68:71]
	v_mfma_f32_16x16x32_bf16 v[64:67], v[156:159], v[188:191], v[64:67]
	s_setprio 0
	s_barrier
	s_add_i32 s4, s28, s2
	v_lshl_add_u64 v[192:193], v[192:193], 0, s[12:13]
	s_mov_b32 m0, s4
	ds_read_b128 v[160:163], v251 offset:49152
	ds_read_b128 v[164:167], v251 offset:50176
	ds_read_b128 v[168:171], v251 offset:51200
	ds_read_b128 v[172:175], v251 offset:52224
	ds_read_b128 v[176:179], v251 offset:53248
	ds_read_b128 v[180:183], v251 offset:54272
	ds_read_b128 v[184:187], v251 offset:55296
	ds_read_b128 v[188:191], v251 offset:56320
	global_load_lds_dwordx4 v[192:193], off
	v_lshl_add_u64 v[192:193], v[194:195], 0, s[12:13]
	s_add_i32 m0, s4, 0x2000
	s_add_i32 s4, s29, s2
	global_load_lds_dwordx4 v[192:193], off
	v_lshl_add_u64 v[192:193], v[196:197], 0, s[12:13]
	s_mov_b32 m0, s4
	s_nop 0
	global_load_lds_dwordx4 v[192:193], off
	v_lshl_add_u64 v[192:193], v[198:199], 0, s[12:13]
	s_add_i32 m0, s4, 0x2000
	s_nop 0
	global_load_lds_dwordx4 v[192:193], off
	v_lshl_add_u64 v[192:193], v[220:221], 0, s[12:13]
	s_mov_b32 m0, s55
	s_nop 0
	global_load_lds_dwordx4 v[192:193], off
	v_lshl_add_u64 v[192:193], v[222:223], 0, s[12:13]
	s_mov_b32 m0, s56
	s_nop 0
	global_load_lds_dwordx4 v[192:193], off
	s_waitcnt vmcnt(8)
	s_waitcnt lgkmcnt(0)
	s_barrier
	s_setprio 1
	v_mfma_f32_16x16x32_bf16 v[60:63], v[88:91], v[160:163], v[60:63]
	v_mfma_f32_16x16x32_bf16 v[56:59], v[96:99], v[160:163], v[56:59]
	v_mfma_f32_16x16x32_bf16 v[44:47], v[88:91], v[168:171], v[44:47]
	v_mfma_f32_16x16x32_bf16 v[40:43], v[96:99], v[168:171], v[40:43]
	v_mfma_f32_16x16x32_bf16 v[28:31], v[88:91], v[176:179], v[28:31]
	v_mfma_f32_16x16x32_bf16 v[24:27], v[96:99], v[176:179], v[24:27]
	v_mfma_f32_16x16x32_bf16 v[12:15], v[88:91], v[184:187], v[12:15]
	v_mfma_f32_16x16x32_bf16 v[8:11], v[96:99], v[184:187], v[8:11]
	v_mfma_f32_16x16x32_bf16 v[60:63], v[92:95], v[164:167], v[60:63]
	v_mfma_f32_16x16x32_bf16 v[56:59], v[100:103], v[164:167], v[56:59]
	v_mfma_f32_16x16x32_bf16 v[44:47], v[92:95], v[172:175], v[44:47]
	v_mfma_f32_16x16x32_bf16 v[40:43], v[100:103], v[172:175], v[40:43]
	v_mfma_f32_16x16x32_bf16 v[28:31], v[92:95], v[180:183], v[28:31]
	v_mfma_f32_16x16x32_bf16 v[24:27], v[100:103], v[180:183], v[24:27]
	v_mfma_f32_16x16x32_bf16 v[12:15], v[92:95], v[188:191], v[12:15]
	v_mfma_f32_16x16x32_bf16 v[8:11], v[100:103], v[188:191], v[8:11]
	v_mfma_f32_16x16x32_bf16 v[52:55], v[144:147], v[160:163], v[52:55]
	v_mfma_f32_16x16x32_bf16 v[48:51], v[152:155], v[160:163], v[48:51]
	v_mfma_f32_16x16x32_bf16 v[36:39], v[144:147], v[168:171], v[36:39]
	v_mfma_f32_16x16x32_bf16 v[32:35], v[152:155], v[168:171], v[32:35]
	v_mfma_f32_16x16x32_bf16 v[20:23], v[144:147], v[176:179], v[20:23]
	v_mfma_f32_16x16x32_bf16 v[16:19], v[152:155], v[176:179], v[16:19]
	v_mfma_f32_16x16x32_bf16 v[4:7], v[144:147], v[184:187], v[4:7]
	v_mfma_f32_16x16x32_bf16 v[0:3], v[152:155], v[184:187], v[0:3]
	v_mfma_f32_16x16x32_bf16 v[52:55], v[148:151], v[164:167], v[52:55]
	v_mfma_f32_16x16x32_bf16 v[48:51], v[156:159], v[164:167], v[48:51]
	v_mfma_f32_16x16x32_bf16 v[36:39], v[148:151], v[172:175], v[36:39]
	v_mfma_f32_16x16x32_bf16 v[32:35], v[156:159], v[172:175], v[32:35]
	v_mfma_f32_16x16x32_bf16 v[20:23], v[148:151], v[180:183], v[20:23]
	v_mfma_f32_16x16x32_bf16 v[16:19], v[156:159], v[180:183], v[16:19]
	v_mfma_f32_16x16x32_bf16 v[4:7], v[148:151], v[188:191], v[4:7]
	v_mfma_f32_16x16x32_bf16 v[0:3], v[156:159], v[188:191], v[0:3]
	s_setprio 0
	s_barrier
	s_add_u32 s0, s0, 0x100
	s_addc_u32 s1, s1, 0
	s_add_u32 s21, s21, 0x100
	s_addc_u32 s22, s22, 0
	s_cmp_ge_u32 s25, s62
	s_mov_b32 s4, s25
	s_cbranch_scc1 .Lpeel_exit_183
.LBB0_183:
	s_add_i32 s25, s4, 2
	s_add_u32 s28, s0, 0x80
	s_addc_u32 s5, s1, 0
	s_add_i32 s36, 0, 0x10000
	s_cmp_eq_u32 s63, s4
	s_cselect_b32 s5, s49, s5
	s_cselect_b32 s4, s48, s28
	s_cselect_b32 s29, s51, s22
	s_cselect_b32 s28, s50, s21
	s_add_i32 s37, 0, 0x14000
	v_add_u32_e32 v100, s36, v249
	v_add_u32_e32 v156, s37, v249
	ds_read_b128 v[88:91], v100
	ds_read_b128 v[92:95], v100 offset:1024
	ds_read_b128 v[96:99], v100 offset:2048
	ds_read_b128 v[100:103], v100 offset:3072
	s_waitcnt lgkmcnt(0)
	ds_read_b128 v[144:147], v156
	ds_read_b128 v[148:151], v156 offset:1024
	ds_read_b128 v[152:155], v156 offset:2048
	ds_read_b128 v[156:159], v156 offset:3072
	v_lshl_add_u64 v[192:193], s[0:1], 0, v[216:217]
	s_add_i32 m0, s3, 0xc000
	ds_read_b128 v[160:163], v251
	ds_read_b128 v[164:167], v251 offset:1024
	ds_read_b128 v[168:171], v251 offset:2048
	ds_read_b128 v[172:175], v251 offset:3072
	ds_read_b128 v[176:179], v251 offset:4096
	ds_read_b128 v[180:183], v251 offset:5120
	ds_read_b128 v[184:187], v251 offset:6144
	ds_read_b128 v[188:191], v251 offset:7168
	global_load_lds_dwordx4 v[192:193], off
	v_lshl_add_u64 v[192:193], s[0:1], 0, v[218:219]
	s_add_i32 m0, s3, 0xe000
	s_nop 0
	global_load_lds_dwordx4 v[192:193], off
	s_waitcnt vmcnt(8)
	s_waitcnt lgkmcnt(0)
	s_barrier
	s_setprio 1
	v_mfma_f32_16x16x32_bf16 v[140:143], v[88:91], v[160:163], v[140:143]
	v_mfma_f32_16x16x32_bf16 v[136:139], v[96:99], v[160:163], v[136:139]
	v_mfma_f32_16x16x32_bf16 v[124:127], v[88:91], v[168:171], v[124:127]
	v_mfma_f32_16x16x32_bf16 v[120:123], v[96:99], v[168:171], v[120:123]
	v_mfma_f32_16x16x32_bf16 v[108:111], v[88:91], v[176:179], v[108:111]
	v_mfma_f32_16x16x32_bf16 v[104:107], v[96:99], v[176:179], v[104:107]
	v_mfma_f32_16x16x32_bf16 v[76:79], v[88:91], v[184:187], v[76:79]
	v_mfma_f32_16x16x32_bf16 v[72:75], v[96:99], v[184:187], v[72:75]
	v_mfma_f32_16x16x32_bf16 v[140:143], v[92:95], v[164:167], v[140:143]
	v_mfma_f32_16x16x32_bf16 v[136:139], v[100:103], v[164:167], v[136:139]
	v_mfma_f32_16x16x32_bf16 v[124:127], v[92:95], v[172:175], v[124:127]
	v_mfma_f32_16x16x32_bf16 v[120:123], v[100:103], v[172:175], v[120:123]
	v_mfma_f32_16x16x32_bf16 v[108:111], v[92:95], v[180:183], v[108:111]
	v_mfma_f32_16x16x32_bf16 v[104:107], v[100:103], v[180:183], v[104:107]
	v_mfma_f32_16x16x32_bf16 v[76:79], v[92:95], v[188:191], v[76:79]
	v_mfma_f32_16x16x32_bf16 v[72:75], v[100:103], v[188:191], v[72:75]
	v_mfma_f32_16x16x32_bf16 v[132:135], v[144:147], v[160:163], v[132:135]
	v_mfma_f32_16x16x32_bf16 v[128:131], v[152:155], v[160:163], v[128:131]
	v_mfma_f32_16x16x32_bf16 v[116:119], v[144:147], v[168:171], v[116:119]
	v_mfma_f32_16x16x32_bf16 v[112:115], v[152:155], v[168:171], v[112:115]
	v_mfma_f32_16x16x32_bf16 v[84:87], v[144:147], v[176:179], v[84:87]
	v_mfma_f32_16x16x32_bf16 v[80:83], v[152:155], v[176:179], v[80:83]
	v_mfma_f32_16x16x32_bf16 v[68:71], v[144:147], v[184:187], v[68:71]
	v_mfma_f32_16x16x32_bf16 v[64:67], v[152:155], v[184:187], v[64:67]
	v_mfma_f32_16x16x32_bf16 v[132:135], v[148:151], v[164:167], v[132:135]
	v_mfma_f32_16x16x32_bf16 v[128:131], v[156:159], v[164:167], v[128:131]
	v_mfma_f32_16x16x32_bf16 v[116:119], v[148:151], v[172:175], v[116:119]
	v_mfma_f32_16x16x32_bf16 v[112:115], v[156:159], v[172:175], v[112:115]
	v_mfma_f32_16x16x32_bf16 v[84:87], v[148:151], v[180:183], v[84:87]
	v_mfma_f32_16x16x32_bf16 v[80:83], v[156:159], v[180:183], v[80:83]
	v_mfma_f32_16x16x32_bf16 v[68:71], v[148:151], v[188:191], v[68:71]
	v_mfma_f32_16x16x32_bf16 v[64:67], v[156:159], v[188:191], v[64:67]
	s_setprio 0
	s_barrier
	s_add_i32 s36, s36, s2
	v_lshl_add_u64 v[192:193], s[28:29], 0, v[204:205]
	s_mov_b32 m0, s36
	ds_read_b128 v[160:163], v251 offset:16384
	ds_read_b128 v[164:167], v251 offset:17408
	ds_read_b128 v[168:171], v251 offset:18432
	ds_read_b128 v[172:175], v251 offset:19456
	ds_read_b128 v[176:179], v251 offset:20480
	ds_read_b128 v[180:183], v251 offset:21504
	ds_read_b128 v[184:187], v251 offset:22528
	ds_read_b128 v[188:191], v251 offset:23552
	global_load_lds_dwordx4 v[192:193], off
	s_add_i32 m0, s36, 0x2000
	v_lshl_add_u64 v[194:195], s[28:29], 0, v[210:211]
	s_add_u32 s28, s28, s10
	s_addc_u32 s29, s29, 0
	s_add_i32 s36, s37, s2
	global_load_lds_dwordx4 v[194:195], off
	v_lshl_add_u64 v[196:197], s[28:29], 0, v[204:205]
	s_mov_b32 m0, s36
	v_lshl_add_u64 v[198:199], s[28:29], 0, v[210:211]
	global_load_lds_dwordx4 v[196:197], off
	s_add_i32 m0, s36, 0x2000
	v_lshl_add_u64 v[220:221], s[4:5], 0, v[214:215]
	global_load_lds_dwordx4 v[198:199], off
	s_mov_b32 m0, s3
	v_lshl_add_u64 v[222:223], s[4:5], 0, v[212:213]
	global_load_lds_dwordx4 v[220:221], off
	s_mov_b32 m0, s52
	s_nop 0
	global_load_lds_dwordx4 v[222:223], off
	s_waitcnt vmcnt(8)
	s_waitcnt lgkmcnt(0)
	s_barrier
	s_setprio 1
	v_mfma_f32_16x16x32_bf16 v[60:63], v[88:91], v[160:163], v[60:63]
	v_mfma_f32_16x16x32_bf16 v[56:59], v[96:99], v[160:163], v[56:59]
	v_mfma_f32_16x16x32_bf16 v[44:47], v[88:91], v[168:171], v[44:47]
	v_mfma_f32_16x16x32_bf16 v[40:43], v[96:99], v[168:171], v[40:43]
	v_mfma_f32_16x16x32_bf16 v[28:31], v[88:91], v[176:179], v[28:31]
	v_mfma_f32_16x16x32_bf16 v[24:27], v[96:99], v[176:179], v[24:27]
	v_mfma_f32_16x16x32_bf16 v[12:15], v[88:91], v[184:187], v[12:15]
	v_mfma_f32_16x16x32_bf16 v[8:11], v[96:99], v[184:187], v[8:11]
	v_mfma_f32_16x16x32_bf16 v[60:63], v[92:95], v[164:167], v[60:63]
	v_mfma_f32_16x16x32_bf16 v[56:59], v[100:103], v[164:167], v[56:59]
	v_mfma_f32_16x16x32_bf16 v[44:47], v[92:95], v[172:175], v[44:47]
	v_mfma_f32_16x16x32_bf16 v[40:43], v[100:103], v[172:175], v[40:43]
	v_mfma_f32_16x16x32_bf16 v[28:31], v[92:95], v[180:183], v[28:31]
	v_mfma_f32_16x16x32_bf16 v[24:27], v[100:103], v[180:183], v[24:27]
	v_mfma_f32_16x16x32_bf16 v[12:15], v[92:95], v[188:191], v[12:15]
	v_mfma_f32_16x16x32_bf16 v[8:11], v[100:103], v[188:191], v[8:11]
	v_mfma_f32_16x16x32_bf16 v[52:55], v[144:147], v[160:163], v[52:55]
	v_mfma_f32_16x16x32_bf16 v[48:51], v[152:155], v[160:163], v[48:51]
	v_mfma_f32_16x16x32_bf16 v[36:39], v[144:147], v[168:171], v[36:39]
	v_mfma_f32_16x16x32_bf16 v[32:35], v[152:155], v[168:171], v[32:35]
	v_mfma_f32_16x16x32_bf16 v[20:23], v[144:147], v[176:179], v[20:23]
	v_mfma_f32_16x16x32_bf16 v[16:19], v[152:155], v[176:179], v[16:19]
	v_mfma_f32_16x16x32_bf16 v[4:7], v[144:147], v[184:187], v[4:7]
	v_mfma_f32_16x16x32_bf16 v[0:3], v[152:155], v[184:187], v[0:3]
	v_mfma_f32_16x16x32_bf16 v[52:55], v[148:151], v[164:167], v[52:55]
	v_mfma_f32_16x16x32_bf16 v[48:51], v[156:159], v[164:167], v[48:51]
	v_mfma_f32_16x16x32_bf16 v[36:39], v[148:151], v[172:175], v[36:39]
	v_mfma_f32_16x16x32_bf16 v[32:35], v[156:159], v[172:175], v[32:35]
	v_mfma_f32_16x16x32_bf16 v[20:23], v[148:151], v[180:183], v[20:23]
	v_mfma_f32_16x16x32_bf16 v[16:19], v[156:159], v[180:183], v[16:19]
	v_mfma_f32_16x16x32_bf16 v[4:7], v[148:151], v[188:191], v[4:7]
	v_mfma_f32_16x16x32_bf16 v[0:3], v[156:159], v[188:191], v[0:3]
	s_setprio 0
	s_barrier
	s_add_i32 s28, 0, 0x18000
	s_add_i32 s29, 0, 0x1c000
	v_add_u32_e32 v100, s28, v249
	v_add_u32_e32 v156, s29, v249
	ds_read_b128 v[88:91], v100
	ds_read_b128 v[92:95], v100 offset:1024
	ds_read_b128 v[96:99], v100 offset:2048
	ds_read_b128 v[100:103], v100 offset:3072
	ds_read_b128 v[144:147], v156
	ds_read_b128 v[148:151], v156 offset:1024
	ds_read_b128 v[152:155], v156 offset:2048
	ds_read_b128 v[156:159], v156 offset:3072
	s_add_u32 s4, s4, s10
	s_addc_u32 s5, s5, 0
	s_mov_b32 m0, s53
	v_lshl_add_u64 v[224:225], s[4:5], 0, v[214:215]
	ds_read_b128 v[160:163], v251 offset:32768
	ds_read_b128 v[164:167], v251 offset:33792
	ds_read_b128 v[168:171], v251 offset:34816
	ds_read_b128 v[172:175], v251 offset:35840
	ds_read_b128 v[176:179], v251 offset:36864
	ds_read_b128 v[180:183], v251 offset:37888
	ds_read_b128 v[184:187], v251 offset:38912
	ds_read_b128 v[188:191], v251 offset:39936
	global_load_lds_dwordx4 v[224:225], off
	v_lshl_add_u64 v[224:225], s[4:5], 0, v[212:213]
	s_mov_b32 m0, s54
	s_nop 0
	global_load_lds_dwordx4 v[224:225], off
	s_waitcnt vmcnt(8)
	s_waitcnt lgkmcnt(0)
	s_barrier
	s_setprio 1
	v_mfma_f32_16x16x32_bf16 v[140:143], v[88:91], v[160:163], v[140:143]
	v_mfma_f32_16x16x32_bf16 v[136:139], v[96:99], v[160:163], v[136:139]
	v_mfma_f32_16x16x32_bf16 v[124:127], v[88:91], v[168:171], v[124:127]
	v_mfma_f32_16x16x32_bf16 v[120:123], v[96:99], v[168:171], v[120:123]
	v_mfma_f32_16x16x32_bf16 v[108:111], v[88:91], v[176:179], v[108:111]
	v_mfma_f32_16x16x32_bf16 v[104:107], v[96:99], v[176:179], v[104:107]
	v_mfma_f32_16x16x32_bf16 v[76:79], v[88:91], v[184:187], v[76:79]
	v_mfma_f32_16x16x32_bf16 v[72:75], v[96:99], v[184:187], v[72:75]
	v_mfma_f32_16x16x32_bf16 v[140:143], v[92:95], v[164:167], v[140:143]
	v_mfma_f32_16x16x32_bf16 v[136:139], v[100:103], v[164:167], v[136:139]
	v_mfma_f32_16x16x32_bf16 v[124:127], v[92:95], v[172:175], v[124:127]
	v_mfma_f32_16x16x32_bf16 v[120:123], v[100:103], v[172:175], v[120:123]
	v_mfma_f32_16x16x32_bf16 v[108:111], v[92:95], v[180:183], v[108:111]
	v_mfma_f32_16x16x32_bf16 v[104:107], v[100:103], v[180:183], v[104:107]
	v_mfma_f32_16x16x32_bf16 v[76:79], v[92:95], v[188:191], v[76:79]
	v_mfma_f32_16x16x32_bf16 v[72:75], v[100:103], v[188:191], v[72:75]
	v_mfma_f32_16x16x32_bf16 v[132:135], v[144:147], v[160:163], v[132:135]
	v_mfma_f32_16x16x32_bf16 v[128:131], v[152:155], v[160:163], v[128:131]
	v_mfma_f32_16x16x32_bf16 v[116:119], v[144:147], v[168:171], v[116:119]
	v_mfma_f32_16x16x32_bf16 v[112:115], v[152:155], v[168:171], v[112:115]
	v_mfma_f32_16x16x32_bf16 v[84:87], v[144:147], v[176:179], v[84:87]
	v_mfma_f32_16x16x32_bf16 v[80:83], v[152:155], v[176:179], v[80:83]
	v_mfma_f32_16x16x32_bf16 v[68:71], v[144:147], v[184:187], v[68:71]
	v_mfma_f32_16x16x32_bf16 v[64:67], v[152:155], v[184:187], v[64:67]
	v_mfma_f32_16x16x32_bf16 v[132:135], v[148:151], v[164:167], v[132:135]
	v_mfma_f32_16x16x32_bf16 v[128:131], v[156:159], v[164:167], v[128:131]
	v_mfma_f32_16x16x32_bf16 v[116:119], v[148:151], v[172:175], v[116:119]
	v_mfma_f32_16x16x32_bf16 v[112:115], v[156:159], v[172:175], v[112:115]
	v_mfma_f32_16x16x32_bf16 v[84:87], v[148:151], v[180:183], v[84:87]
	v_mfma_f32_16x16x32_bf16 v[80:83], v[156:159], v[180:183], v[80:83]
	v_mfma_f32_16x16x32_bf16 v[68:71], v[148:151], v[188:191], v[68:71]
	v_mfma_f32_16x16x32_bf16 v[64:67], v[156:159], v[188:191], v[64:67]
	s_setprio 0
	s_barrier
	s_add_i32 s4, s28, s2
	v_lshl_add_u64 v[192:193], v[192:193], 0, s[12:13]
	s_mov_b32 m0, s4
	ds_read_b128 v[160:163], v251 offset:49152
	ds_read_b128 v[164:167], v251 offset:50176
	ds_read_b128 v[168:171], v251 offset:51200
	ds_read_b128 v[172:175], v251 offset:52224
	ds_read_b128 v[176:179], v251 offset:53248
	ds_read_b128 v[180:183], v251 offset:54272
	ds_read_b128 v[184:187], v251 offset:55296
	ds_read_b128 v[188:191], v251 offset:56320
	global_load_lds_dwordx4 v[192:193], off
	v_lshl_add_u64 v[192:193], v[194:195], 0, s[12:13]
	s_add_i32 m0, s4, 0x2000
	s_add_i32 s4, s29, s2
	global_load_lds_dwordx4 v[192:193], off
	v_lshl_add_u64 v[192:193], v[196:197], 0, s[12:13]
	s_mov_b32 m0, s4
	s_nop 0
	global_load_lds_dwordx4 v[192:193], off
	v_lshl_add_u64 v[192:193], v[198:199], 0, s[12:13]
	s_add_i32 m0, s4, 0x2000
	s_nop 0
	global_load_lds_dwordx4 v[192:193], off
	v_lshl_add_u64 v[192:193], v[220:221], 0, s[12:13]
	s_mov_b32 m0, s55
	s_nop 0
	global_load_lds_dwordx4 v[192:193], off
	v_lshl_add_u64 v[192:193], v[222:223], 0, s[12:13]
	s_mov_b32 m0, s56
	s_nop 0
	global_load_lds_dwordx4 v[192:193], off
	s_waitcnt vmcnt(8)
	s_waitcnt lgkmcnt(0)
	s_barrier
	s_setprio 1
	v_mfma_f32_16x16x32_bf16 v[60:63], v[88:91], v[160:163], v[60:63]
	v_mfma_f32_16x16x32_bf16 v[56:59], v[96:99], v[160:163], v[56:59]
	v_mfma_f32_16x16x32_bf16 v[44:47], v[88:91], v[168:171], v[44:47]
	v_mfma_f32_16x16x32_bf16 v[40:43], v[96:99], v[168:171], v[40:43]
	v_mfma_f32_16x16x32_bf16 v[28:31], v[88:91], v[176:179], v[28:31]
	v_mfma_f32_16x16x32_bf16 v[24:27], v[96:99], v[176:179], v[24:27]
	v_mfma_f32_16x16x32_bf16 v[12:15], v[88:91], v[184:187], v[12:15]
	v_mfma_f32_16x16x32_bf16 v[8:11], v[96:99], v[184:187], v[8:11]
	v_mfma_f32_16x16x32_bf16 v[60:63], v[92:95], v[164:167], v[60:63]
	v_mfma_f32_16x16x32_bf16 v[56:59], v[100:103], v[164:167], v[56:59]
	v_mfma_f32_16x16x32_bf16 v[44:47], v[92:95], v[172:175], v[44:47]
	v_mfma_f32_16x16x32_bf16 v[40:43], v[100:103], v[172:175], v[40:43]
	v_mfma_f32_16x16x32_bf16 v[28:31], v[92:95], v[180:183], v[28:31]
	v_mfma_f32_16x16x32_bf16 v[24:27], v[100:103], v[180:183], v[24:27]
	v_mfma_f32_16x16x32_bf16 v[12:15], v[92:95], v[188:191], v[12:15]
	v_mfma_f32_16x16x32_bf16 v[8:11], v[100:103], v[188:191], v[8:11]
	v_mfma_f32_16x16x32_bf16 v[52:55], v[144:147], v[160:163], v[52:55]
	v_mfma_f32_16x16x32_bf16 v[48:51], v[152:155], v[160:163], v[48:51]
	v_mfma_f32_16x16x32_bf16 v[36:39], v[144:147], v[168:171], v[36:39]
	v_mfma_f32_16x16x32_bf16 v[32:35], v[152:155], v[168:171], v[32:35]
	v_mfma_f32_16x16x32_bf16 v[20:23], v[144:147], v[176:179], v[20:23]
	v_mfma_f32_16x16x32_bf16 v[16:19], v[152:155], v[176:179], v[16:19]
	v_mfma_f32_16x16x32_bf16 v[4:7], v[144:147], v[184:187], v[4:7]
	v_mfma_f32_16x16x32_bf16 v[0:3], v[152:155], v[184:187], v[0:3]
	v_mfma_f32_16x16x32_bf16 v[52:55], v[148:151], v[164:167], v[52:55]
	v_mfma_f32_16x16x32_bf16 v[48:51], v[156:159], v[164:167], v[48:51]
	v_mfma_f32_16x16x32_bf16 v[36:39], v[148:151], v[172:175], v[36:39]
	v_mfma_f32_16x16x32_bf16 v[32:35], v[156:159], v[172:175], v[32:35]
	v_mfma_f32_16x16x32_bf16 v[20:23], v[148:151], v[180:183], v[20:23]
	v_mfma_f32_16x16x32_bf16 v[16:19], v[156:159], v[180:183], v[16:19]
	v_mfma_f32_16x16x32_bf16 v[4:7], v[148:151], v[188:191], v[4:7]
	v_mfma_f32_16x16x32_bf16 v[0:3], v[156:159], v[188:191], v[0:3]
	s_setprio 0
	s_barrier
	s_add_u32 s0, s0, 0x100
	s_addc_u32 s1, s1, 0
	s_add_u32 s21, s21, 0x100
	s_addc_u32 s22, s22, 0
	s_cmp_ge_u32 s25, s62
	s_mov_b32 s4, s25
	s_cbranch_scc0 .LBB0_183

.LBB0_317:
	s_add_u32 s25, s0, 0x100
	s_addc_u32 s66, s1, 0
	s_ashr_i32 s39, s38, 31
	s_lshl_b64 s[36:37], s[38:39], 20
	s_add_u32 s42, s16, s36
	s_addc_u32 s43, s17, s37
	s_and_b64 s[36:37], s[62:63], exec
	s_cselect_b32 s39, s43, s3
	s_cselect_b32 s67, s42, s2
	s_ashr_i32 s35, s34, 31
	s_lshl_b64 s[36:37], s[34:35], 20
	s_add_u32 s40, s46, s36
	s_addc_u32 s41, s47, s37
	s_and_b64 s[36:37], s[62:63], exec
	s_cselect_b32 s35, s41, s1
	s_cselect_b32 s70, s40, s0
	s_add_u32 s0, s2, 0x80080
	s_addc_u32 s1, s3, 0
	v_lshl_add_u64 v[128:129], s[0:1], 0, v[150:151]
	v_lshl_add_u64 v[130:131], s[0:1], 0, v[152:153]
	s_mov_b32 s71, -2
	s_mov_b64 s[0:1], 0
	s_add_u32 s36, s2, s0
	s_addc_u32 s37, s3, s1
	s_add_u32 s36, s36, 0x100
	s_addc_u32 s37, s37, 0
	s_add_u32 s72, s25, s0
	s_addc_u32 s73, s66, s1
	s_add_i32 s74, 0, 0x10000
	s_cmpk_eq_i32 s0, 0xf00
	s_cselect_b32 s45, s39, s37
	s_cselect_b32 s44, s67, s36
	v_add_u32_e32 v154, s74, v159
	s_cselect_b32 s37, s35, s73
	s_cselect_b32 s36, s70, s72
	s_add_i32 s75, 0, 0x14000
	ds_read_b128 v[132:135], v154
	ds_read_b128 v[136:139], v154 offset:1024
	ds_read_b128 v[140:143], v154 offset:2048
	ds_read_b128 v[166:169], v154 offset:3072
	v_add_u32_e32 v154, s75, v159
	ds_read_b128 v[170:173], v154
	ds_read_b128 v[174:177], v154 offset:1024
	ds_read_b128 v[178:181], v154 offset:2048
	ds_read_b128 v[182:185], v154 offset:3072
	v_lshl_add_u64 v[154:155], v[128:129], 0, s[0:1]
	s_add_i32 m0, s7, 0xc000
	ds_read_b128 v[186:189], v165
	ds_read_b128 v[190:193], v165 offset:1024
	ds_read_b128 v[194:197], v165 offset:2048
	ds_read_b128 v[210:213], v165 offset:3072
	ds_read_b128 v[214:217], v165 offset:4096
	ds_read_b128 v[218:221], v165 offset:5120
	ds_read_b128 v[222:225], v165 offset:6144
	ds_read_b128 v[226:229], v165 offset:7168
	global_load_lds_dwordx4 v[154:155], off
	v_lshl_add_u64 v[154:155], v[130:131], 0, s[0:1]
	s_add_i32 m0, s7, 0xe000
	s_nop 0
	global_load_lds_dwordx4 v[154:155], off
	s_waitcnt vmcnt(8)
	s_waitcnt lgkmcnt(0)
	s_barrier
	s_setprio 1
	v_mfma_f32_16x16x32_bf16 v[124:127], v[132:135], v[186:189], 0
	v_mfma_f32_16x16x32_bf16 v[120:123], v[140:143], v[186:189], 0
	v_mfma_f32_16x16x32_bf16 v[116:119], v[132:135], v[194:197], 0
	v_mfma_f32_16x16x32_bf16 v[112:115], v[140:143], v[194:197], 0
	v_mfma_f32_16x16x32_bf16 v[108:111], v[132:135], v[214:217], 0
	v_mfma_f32_16x16x32_bf16 v[104:107], v[140:143], v[214:217], 0
	v_mfma_f32_16x16x32_bf16 v[100:103], v[132:135], v[222:225], 0
	v_mfma_f32_16x16x32_bf16 v[96:99], v[140:143], v[222:225], 0
	v_mfma_f32_16x16x32_bf16 v[124:127], v[136:139], v[190:193], v[124:127]
	v_mfma_f32_16x16x32_bf16 v[120:123], v[166:169], v[190:193], v[120:123]
	v_mfma_f32_16x16x32_bf16 v[116:119], v[136:139], v[210:213], v[116:119]
	v_mfma_f32_16x16x32_bf16 v[112:115], v[166:169], v[210:213], v[112:115]
	v_mfma_f32_16x16x32_bf16 v[108:111], v[136:139], v[218:221], v[108:111]
	v_mfma_f32_16x16x32_bf16 v[104:107], v[166:169], v[218:221], v[104:107]
	v_mfma_f32_16x16x32_bf16 v[100:103], v[136:139], v[226:229], v[100:103]
	v_mfma_f32_16x16x32_bf16 v[96:99], v[166:169], v[226:229], v[96:99]
	v_mfma_f32_16x16x32_bf16 v[92:95], v[170:173], v[186:189], 0
	v_mfma_f32_16x16x32_bf16 v[88:91], v[178:181], v[186:189], 0
	v_mfma_f32_16x16x32_bf16 v[84:87], v[170:173], v[194:197], 0
	v_mfma_f32_16x16x32_bf16 v[80:83], v[178:181], v[194:197], 0
	v_mfma_f32_16x16x32_bf16 v[76:79], v[170:173], v[214:217], 0
	v_mfma_f32_16x16x32_bf16 v[72:75], v[178:181], v[214:217], 0
	v_mfma_f32_16x16x32_bf16 v[68:71], v[170:173], v[222:225], 0
	v_mfma_f32_16x16x32_bf16 v[64:67], v[178:181], v[222:225], 0
	v_mfma_f32_16x16x32_bf16 v[92:95], v[174:177], v[190:193], v[92:95]
	v_mfma_f32_16x16x32_bf16 v[88:91], v[182:185], v[190:193], v[88:91]
	v_mfma_f32_16x16x32_bf16 v[84:87], v[174:177], v[210:213], v[84:87]
	v_mfma_f32_16x16x32_bf16 v[80:83], v[182:185], v[210:213], v[80:83]
	v_mfma_f32_16x16x32_bf16 v[76:79], v[174:177], v[218:221], v[76:79]
	v_mfma_f32_16x16x32_bf16 v[72:75], v[182:185], v[218:221], v[72:75]
	v_mfma_f32_16x16x32_bf16 v[68:71], v[174:177], v[226:229], v[68:71]
	v_mfma_f32_16x16x32_bf16 v[64:67], v[182:185], v[226:229], v[64:67]
	s_setprio 0
	s_barrier
	s_add_i32 s72, s74, s29
	v_lshl_add_u64 v[154:155], s[36:37], 0, v[204:205]
	s_mov_b32 m0, s72
	ds_read_b128 v[186:189], v165 offset:16384
	ds_read_b128 v[190:193], v165 offset:17408
	ds_read_b128 v[194:197], v165 offset:18432
	ds_read_b128 v[210:213], v165 offset:19456
	ds_read_b128 v[214:217], v165 offset:20480
	ds_read_b128 v[218:221], v165 offset:21504
	ds_read_b128 v[222:225], v165 offset:22528
	ds_read_b128 v[226:229], v165 offset:23552
	global_load_lds_dwordx4 v[154:155], off
	s_add_i32 m0, s72, 0x2000
	s_add_u32 s72, s36, 0x80000
	v_lshl_add_u64 v[198:199], s[36:37], 0, v[148:149]
	s_addc_u32 s73, s37, 0
	s_add_i32 s74, s75, s29
	global_load_lds_dwordx4 v[198:199], off
	v_lshl_add_u64 v[230:231], s[72:73], 0, v[204:205]
	s_mov_b32 m0, s74
	v_lshl_add_u64 v[232:233], s[44:45], 0, v[146:147]
	global_load_lds_dwordx4 v[230:231], off
	v_lshl_add_u64 v[230:231], s[72:73], 0, v[148:149]
	s_add_i32 m0, s74, 0x2000
	s_nop 0
	global_load_lds_dwordx4 v[230:231], off
	v_lshl_add_u64 v[230:231], s[44:45], 0, v[144:145]
	s_mov_b32 m0, s7
	s_nop 0
	global_load_lds_dwordx4 v[230:231], off
	s_mov_b32 m0, s9
	s_nop 0
	global_load_lds_dwordx4 v[232:233], off
	s_waitcnt vmcnt(8)
	s_waitcnt lgkmcnt(0)
	s_barrier
	s_setprio 1
	v_mfma_f32_16x16x32_bf16 v[60:63], v[132:135], v[186:189], 0
	v_mfma_f32_16x16x32_bf16 v[56:59], v[140:143], v[186:189], 0
	v_mfma_f32_16x16x32_bf16 v[52:55], v[132:135], v[194:197], 0
	v_mfma_f32_16x16x32_bf16 v[48:51], v[140:143], v[194:197], 0
	v_mfma_f32_16x16x32_bf16 v[44:47], v[132:135], v[214:217], 0
	v_mfma_f32_16x16x32_bf16 v[40:43], v[140:143], v[214:217], 0
	v_mfma_f32_16x16x32_bf16 v[36:39], v[132:135], v[222:225], 0
	v_mfma_f32_16x16x32_bf16 v[32:35], v[140:143], v[222:225], 0
	v_mfma_f32_16x16x32_bf16 v[60:63], v[136:139], v[190:193], v[60:63]
	v_mfma_f32_16x16x32_bf16 v[56:59], v[166:169], v[190:193], v[56:59]
	v_mfma_f32_16x16x32_bf16 v[52:55], v[136:139], v[210:213], v[52:55]
	v_mfma_f32_16x16x32_bf16 v[48:51], v[166:169], v[210:213], v[48:51]
	v_mfma_f32_16x16x32_bf16 v[44:47], v[136:139], v[218:221], v[44:47]
	v_mfma_f32_16x16x32_bf16 v[40:43], v[166:169], v[218:221], v[40:43]
	v_mfma_f32_16x16x32_bf16 v[36:39], v[136:139], v[226:229], v[36:39]
	v_mfma_f32_16x16x32_bf16 v[32:35], v[166:169], v[226:229], v[32:35]
	v_mfma_f32_16x16x32_bf16 v[28:31], v[170:173], v[186:189], 0
	v_mfma_f32_16x16x32_bf16 v[24:27], v[178:181], v[186:189], 0
	v_mfma_f32_16x16x32_bf16 v[20:23], v[170:173], v[194:197], 0
	v_mfma_f32_16x16x32_bf16 v[16:19], v[178:181], v[194:197], 0
	v_mfma_f32_16x16x32_bf16 v[12:15], v[170:173], v[214:217], 0
	v_mfma_f32_16x16x32_bf16 v[8:11], v[178:181], v[214:217], 0
	v_mfma_f32_16x16x32_bf16 v[4:7], v[170:173], v[222:225], 0
	v_mfma_f32_16x16x32_bf16 v[0:3], v[178:181], v[222:225], 0
	v_mfma_f32_16x16x32_bf16 v[28:31], v[174:177], v[190:193], v[28:31]
	v_mfma_f32_16x16x32_bf16 v[24:27], v[182:185], v[190:193], v[24:27]
	v_mfma_f32_16x16x32_bf16 v[20:23], v[174:177], v[210:213], v[20:23]
	v_mfma_f32_16x16x32_bf16 v[16:19], v[182:185], v[210:213], v[16:19]
	v_mfma_f32_16x16x32_bf16 v[12:15], v[174:177], v[218:221], v[12:15]
	v_mfma_f32_16x16x32_bf16 v[8:11], v[182:185], v[218:221], v[8:11]
	v_mfma_f32_16x16x32_bf16 v[4:7], v[174:177], v[226:229], v[4:7]
	v_mfma_f32_16x16x32_bf16 v[0:3], v[182:185], v[226:229], v[0:3]
	s_setprio 0
	s_barrier
	s_add_i32 s72, 0, 0x18000
	v_add_u32_e32 v156, s72, v159
	s_add_i32 s73, 0, 0x1c000
	ds_read_b128 v[132:135], v156
	ds_read_b128 v[136:139], v156 offset:1024
	ds_read_b128 v[140:143], v156 offset:2048
	ds_read_b128 v[166:169], v156 offset:3072
	v_add_u32_e32 v156, s73, v159
	ds_read_b128 v[170:173], v156
	ds_read_b128 v[174:177], v156 offset:1024
	ds_read_b128 v[178:181], v156 offset:2048
	ds_read_b128 v[182:185], v156 offset:3072
	s_add_u32 s44, s44, 0x80000
	s_addc_u32 s45, s45, 0
	s_mov_b32 m0, s49
	v_lshl_add_u64 v[248:249], s[44:45], 0, v[144:145]
	ds_read_b128 v[186:189], v165 offset:32768
	ds_read_b128 v[190:193], v165 offset:33792
	ds_read_b128 v[194:197], v165 offset:34816
	ds_read_b128 v[210:213], v165 offset:35840
	ds_read_b128 v[214:217], v165 offset:36864
	ds_read_b128 v[218:221], v165 offset:37888
	ds_read_b128 v[222:225], v165 offset:38912
	ds_read_b128 v[226:229], v165 offset:39936
	global_load_lds_dwordx4 v[248:249], off
	v_lshl_add_u64 v[248:249], s[44:45], 0, v[146:147]
	s_mov_b32 m0, s50
	s_nop 0
	global_load_lds_dwordx4 v[248:249], off
	s_waitcnt vmcnt(8)
	s_waitcnt lgkmcnt(0)
	s_barrier
	s_setprio 1
	v_mfma_f32_16x16x32_bf16 v[124:127], v[132:135], v[186:189], v[124:127]
	v_mfma_f32_16x16x32_bf16 v[120:123], v[140:143], v[186:189], v[120:123]
	v_mfma_f32_16x16x32_bf16 v[116:119], v[132:135], v[194:197], v[116:119]
	v_mfma_f32_16x16x32_bf16 v[112:115], v[140:143], v[194:197], v[112:115]
	v_mfma_f32_16x16x32_bf16 v[108:111], v[132:135], v[214:217], v[108:111]
	v_mfma_f32_16x16x32_bf16 v[104:107], v[140:143], v[214:217], v[104:107]
	v_mfma_f32_16x16x32_bf16 v[100:103], v[132:135], v[222:225], v[100:103]
	v_mfma_f32_16x16x32_bf16 v[96:99], v[140:143], v[222:225], v[96:99]
	v_mfma_f32_16x16x32_bf16 v[124:127], v[136:139], v[190:193], v[124:127]
	v_mfma_f32_16x16x32_bf16 v[120:123], v[166:169], v[190:193], v[120:123]
	v_mfma_f32_16x16x32_bf16 v[116:119], v[136:139], v[210:213], v[116:119]
	v_mfma_f32_16x16x32_bf16 v[112:115], v[166:169], v[210:213], v[112:115]
	v_mfma_f32_16x16x32_bf16 v[108:111], v[136:139], v[218:221], v[108:111]
	v_mfma_f32_16x16x32_bf16 v[104:107], v[166:169], v[218:221], v[104:107]
	v_mfma_f32_16x16x32_bf16 v[100:103], v[136:139], v[226:229], v[100:103]
	v_mfma_f32_16x16x32_bf16 v[96:99], v[166:169], v[226:229], v[96:99]
	v_mfma_f32_16x16x32_bf16 v[92:95], v[170:173], v[186:189], v[92:95]
	v_mfma_f32_16x16x32_bf16 v[88:91], v[178:181], v[186:189], v[88:91]
	v_mfma_f32_16x16x32_bf16 v[84:87], v[170:173], v[194:197], v[84:87]
	v_mfma_f32_16x16x32_bf16 v[80:83], v[178:181], v[194:197], v[80:83]
	v_mfma_f32_16x16x32_bf16 v[76:79], v[170:173], v[214:217], v[76:79]
	v_mfma_f32_16x16x32_bf16 v[72:75], v[178:181], v[214:217], v[72:75]
	v_mfma_f32_16x16x32_bf16 v[68:71], v[170:173], v[222:225], v[68:71]
	v_mfma_f32_16x16x32_bf16 v[64:67], v[178:181], v[222:225], v[64:67]
	v_mfma_f32_16x16x32_bf16 v[92:95], v[174:177], v[190:193], v[92:95]
	v_mfma_f32_16x16x32_bf16 v[88:91], v[182:185], v[190:193], v[88:91]
	v_mfma_f32_16x16x32_bf16 v[84:87], v[174:177], v[210:213], v[84:87]
	v_mfma_f32_16x16x32_bf16 v[80:83], v[182:185], v[210:213], v[80:83]
	v_mfma_f32_16x16x32_bf16 v[76:79], v[174:177], v[218:221], v[76:79]
	v_mfma_f32_16x16x32_bf16 v[72:75], v[182:185], v[218:221], v[72:75]
	v_mfma_f32_16x16x32_bf16 v[68:71], v[174:177], v[226:229], v[68:71]
	v_mfma_f32_16x16x32_bf16 v[64:67], v[182:185], v[226:229], v[64:67]
	s_setprio 0
	s_barrier
	s_add_i32 s44, s72, s29
	v_lshl_add_u64 v[154:155], v[154:155], 0, s[12:13]
	s_mov_b32 m0, s44
	ds_read_b128 v[186:189], v165 offset:49152
	ds_read_b128 v[190:193], v165 offset:50176
	ds_read_b128 v[194:197], v165 offset:51200
	ds_read_b128 v[210:213], v165 offset:52224
	ds_read_b128 v[214:217], v165 offset:53248
	ds_read_b128 v[218:221], v165 offset:54272
	ds_read_b128 v[222:225], v165 offset:55296
	ds_read_b128 v[226:229], v165 offset:56320
	global_load_lds_dwordx4 v[154:155], off
	s_add_i32 m0, s44, 0x2000
	s_add_u32 s36, s36, 0x80080
	v_lshl_add_u64 v[154:155], v[198:199], 0, s[12:13]
	s_addc_u32 s37, s37, 0
	s_add_i32 s44, s73, s29
	global_load_lds_dwordx4 v[154:155], off
	v_lshl_add_u64 v[154:155], s[36:37], 0, v[204:205]
	s_mov_b32 m0, s44
	s_nop 0
	global_load_lds_dwordx4 v[154:155], off
	v_lshl_add_u64 v[154:155], s[36:37], 0, v[148:149]
	s_add_i32 m0, s44, 0x2000
	s_nop 0
	global_load_lds_dwordx4 v[154:155], off
	v_lshl_add_u64 v[154:155], v[230:231], 0, s[12:13]
	s_mov_b32 m0, s54
	s_nop 0
	global_load_lds_dwordx4 v[154:155], off
	v_lshl_add_u64 v[154:155], v[232:233], 0, s[12:13]
	s_mov_b32 m0, s55
	s_nop 0
	global_load_lds_dwordx4 v[154:155], off
	s_waitcnt vmcnt(8)
	s_waitcnt lgkmcnt(0)
	s_barrier
	s_setprio 1
	v_mfma_f32_16x16x32_bf16 v[60:63], v[132:135], v[186:189], v[60:63]
	v_mfma_f32_16x16x32_bf16 v[56:59], v[140:143], v[186:189], v[56:59]
	v_mfma_f32_16x16x32_bf16 v[52:55], v[132:135], v[194:197], v[52:55]
	v_mfma_f32_16x16x32_bf16 v[48:51], v[140:143], v[194:197], v[48:51]
	v_mfma_f32_16x16x32_bf16 v[44:47], v[132:135], v[214:217], v[44:47]
	v_mfma_f32_16x16x32_bf16 v[40:43], v[140:143], v[214:217], v[40:43]
	v_mfma_f32_16x16x32_bf16 v[36:39], v[132:135], v[222:225], v[36:39]
	v_mfma_f32_16x16x32_bf16 v[32:35], v[140:143], v[222:225], v[32:35]
	v_mfma_f32_16x16x32_bf16 v[60:63], v[136:139], v[190:193], v[60:63]
	v_mfma_f32_16x16x32_bf16 v[56:59], v[166:169], v[190:193], v[56:59]
	v_mfma_f32_16x16x32_bf16 v[52:55], v[136:139], v[210:213], v[52:55]
	v_mfma_f32_16x16x32_bf16 v[48:51], v[166:169], v[210:213], v[48:51]
	v_mfma_f32_16x16x32_bf16 v[44:47], v[136:139], v[218:221], v[44:47]
	v_mfma_f32_16x16x32_bf16 v[40:43], v[166:169], v[218:221], v[40:43]
	v_mfma_f32_16x16x32_bf16 v[36:39], v[136:139], v[226:229], v[36:39]
	v_mfma_f32_16x16x32_bf16 v[32:35], v[166:169], v[226:229], v[32:35]
	v_mfma_f32_16x16x32_bf16 v[28:31], v[170:173], v[186:189], v[28:31]
	v_mfma_f32_16x16x32_bf16 v[24:27], v[178:181], v[186:189], v[24:27]
	v_mfma_f32_16x16x32_bf16 v[20:23], v[170:173], v[194:197], v[20:23]
	v_mfma_f32_16x16x32_bf16 v[16:19], v[178:181], v[194:197], v[16:19]
	v_mfma_f32_16x16x32_bf16 v[12:15], v[170:173], v[214:217], v[12:15]
	v_mfma_f32_16x16x32_bf16 v[8:11], v[178:181], v[214:217], v[8:11]
	v_mfma_f32_16x16x32_bf16 v[4:7], v[170:173], v[222:225], v[4:7]
	v_mfma_f32_16x16x32_bf16 v[0:3], v[178:181], v[222:225], v[0:3]
	v_mfma_f32_16x16x32_bf16 v[28:31], v[174:177], v[190:193], v[28:31]
	v_mfma_f32_16x16x32_bf16 v[24:27], v[182:185], v[190:193], v[24:27]
	v_mfma_f32_16x16x32_bf16 v[20:23], v[174:177], v[210:213], v[20:23]
	v_mfma_f32_16x16x32_bf16 v[16:19], v[182:185], v[210:213], v[16:19]
	v_mfma_f32_16x16x32_bf16 v[12:15], v[174:177], v[218:221], v[12:15]
	v_mfma_f32_16x16x32_bf16 v[8:11], v[182:185], v[218:221], v[8:11]
	v_mfma_f32_16x16x32_bf16 v[4:7], v[174:177], v[226:229], v[4:7]
	v_mfma_f32_16x16x32_bf16 v[0:3], v[182:185], v[226:229], v[0:3]
	s_setprio 0
	s_barrier
	s_add_i32 s71, s71, 2
	s_add_u32 s0, s0, 0x100
	s_addc_u32 s1, s1, 0
	s_cmp_gt_u32 s71, 29
	s_cbranch_scc1 .Lpeel_exit_318
.LBB0_318:
	s_add_u32 s36, s2, s0
	s_addc_u32 s37, s3, s1
	s_add_u32 s36, s36, 0x100
	s_addc_u32 s37, s37, 0
	s_add_u32 s72, s25, s0
	s_addc_u32 s73, s66, s1
	s_add_i32 s74, 0, 0x10000
	s_cmpk_eq_i32 s0, 0xf00
	s_cselect_b32 s45, s39, s37
	s_cselect_b32 s44, s67, s36
	v_add_u32_e32 v154, s74, v159
	s_cselect_b32 s37, s35, s73
	s_cselect_b32 s36, s70, s72
	s_add_i32 s75, 0, 0x14000
	ds_read_b128 v[132:135], v154
	ds_read_b128 v[136:139], v154 offset:1024
	ds_read_b128 v[140:143], v154 offset:2048
	ds_read_b128 v[166:169], v154 offset:3072
	v_add_u32_e32 v154, s75, v159
	ds_read_b128 v[170:173], v154
	ds_read_b128 v[174:177], v154 offset:1024
	ds_read_b128 v[178:181], v154 offset:2048
	ds_read_b128 v[182:185], v154 offset:3072
	v_lshl_add_u64 v[154:155], v[128:129], 0, s[0:1]
	s_add_i32 m0, s7, 0xc000
	ds_read_b128 v[186:189], v165
	ds_read_b128 v[190:193], v165 offset:1024
	ds_read_b128 v[194:197], v165 offset:2048
	ds_read_b128 v[210:213], v165 offset:3072
	ds_read_b128 v[214:217], v165 offset:4096
	ds_read_b128 v[218:221], v165 offset:5120
	ds_read_b128 v[222:225], v165 offset:6144
	ds_read_b128 v[226:229], v165 offset:7168
	global_load_lds_dwordx4 v[154:155], off
	v_lshl_add_u64 v[154:155], v[130:131], 0, s[0:1]
	s_add_i32 m0, s7, 0xe000
	s_nop 0
	global_load_lds_dwordx4 v[154:155], off
	s_waitcnt vmcnt(8)
	s_waitcnt lgkmcnt(0)
	s_barrier
	s_setprio 1
	v_mfma_f32_16x16x32_bf16 v[124:127], v[132:135], v[186:189], v[124:127]
	v_mfma_f32_16x16x32_bf16 v[120:123], v[140:143], v[186:189], v[120:123]
	v_mfma_f32_16x16x32_bf16 v[116:119], v[132:135], v[194:197], v[116:119]
	v_mfma_f32_16x16x32_bf16 v[112:115], v[140:143], v[194:197], v[112:115]
	v_mfma_f32_16x16x32_bf16 v[108:111], v[132:135], v[214:217], v[108:111]
	v_mfma_f32_16x16x32_bf16 v[104:107], v[140:143], v[214:217], v[104:107]
	v_mfma_f32_16x16x32_bf16 v[100:103], v[132:135], v[222:225], v[100:103]
	v_mfma_f32_16x16x32_bf16 v[96:99], v[140:143], v[222:225], v[96:99]
	v_mfma_f32_16x16x32_bf16 v[124:127], v[136:139], v[190:193], v[124:127]
	v_mfma_f32_16x16x32_bf16 v[120:123], v[166:169], v[190:193], v[120:123]
	v_mfma_f32_16x16x32_bf16 v[116:119], v[136:139], v[210:213], v[116:119]
	v_mfma_f32_16x16x32_bf16 v[112:115], v[166:169], v[210:213], v[112:115]
	v_mfma_f32_16x16x32_bf16 v[108:111], v[136:139], v[218:221], v[108:111]
	v_mfma_f32_16x16x32_bf16 v[104:107], v[166:169], v[218:221], v[104:107]
	v_mfma_f32_16x16x32_bf16 v[100:103], v[136:139], v[226:229], v[100:103]
	v_mfma_f32_16x16x32_bf16 v[96:99], v[166:169], v[226:229], v[96:99]
	v_mfma_f32_16x16x32_bf16 v[92:95], v[170:173], v[186:189], v[92:95]
	v_mfma_f32_16x16x32_bf16 v[88:91], v[178:181], v[186:189], v[88:91]
	v_mfma_f32_16x16x32_bf16 v[84:87], v[170:173], v[194:197], v[84:87]
	v_mfma_f32_16x16x32_bf16 v[80:83], v[178:181], v[194:197], v[80:83]
	v_mfma_f32_16x16x32_bf16 v[76:79], v[170:173], v[214:217], v[76:79]
	v_mfma_f32_16x16x32_bf16 v[72:75], v[178:181], v[214:217], v[72:75]
	v_mfma_f32_16x16x32_bf16 v[68:71], v[170:173], v[222:225], v[68:71]
	v_mfma_f32_16x16x32_bf16 v[64:67], v[178:181], v[222:225], v[64:67]
	v_mfma_f32_16x16x32_bf16 v[92:95], v[174:177], v[190:193], v[92:95]
	v_mfma_f32_16x16x32_bf16 v[88:91], v[182:185], v[190:193], v[88:91]
	v_mfma_f32_16x16x32_bf16 v[84:87], v[174:177], v[210:213], v[84:87]
	v_mfma_f32_16x16x32_bf16 v[80:83], v[182:185], v[210:213], v[80:83]
	v_mfma_f32_16x16x32_bf16 v[76:79], v[174:177], v[218:221], v[76:79]
	v_mfma_f32_16x16x32_bf16 v[72:75], v[182:185], v[218:221], v[72:75]
	v_mfma_f32_16x16x32_bf16 v[68:71], v[174:177], v[226:229], v[68:71]
	v_mfma_f32_16x16x32_bf16 v[64:67], v[182:185], v[226:229], v[64:67]
	s_setprio 0
	s_barrier
	s_add_i32 s72, s74, s29
	v_lshl_add_u64 v[154:155], s[36:37], 0, v[204:205]
	s_mov_b32 m0, s72
	ds_read_b128 v[186:189], v165 offset:16384
	ds_read_b128 v[190:193], v165 offset:17408
	ds_read_b128 v[194:197], v165 offset:18432
	ds_read_b128 v[210:213], v165 offset:19456
	ds_read_b128 v[214:217], v165 offset:20480
	ds_read_b128 v[218:221], v165 offset:21504
	ds_read_b128 v[222:225], v165 offset:22528
	ds_read_b128 v[226:229], v165 offset:23552
	global_load_lds_dwordx4 v[154:155], off
	s_add_i32 m0, s72, 0x2000
	s_add_u32 s72, s36, 0x80000
	v_lshl_add_u64 v[198:199], s[36:37], 0, v[148:149]
	s_addc_u32 s73, s37, 0
	s_add_i32 s74, s75, s29
	global_load_lds_dwordx4 v[198:199], off
	v_lshl_add_u64 v[230:231], s[72:73], 0, v[204:205]
	s_mov_b32 m0, s74
	v_lshl_add_u64 v[232:233], s[44:45], 0, v[146:147]
	global_load_lds_dwordx4 v[230:231], off
	v_lshl_add_u64 v[230:231], s[72:73], 0, v[148:149]
	s_add_i32 m0, s74, 0x2000
	s_nop 0
	global_load_lds_dwordx4 v[230:231], off
	v_lshl_add_u64 v[230:231], s[44:45], 0, v[144:145]
	s_mov_b32 m0, s7
	s_nop 0
	global_load_lds_dwordx4 v[230:231], off
	s_mov_b32 m0, s9
	s_nop 0
	global_load_lds_dwordx4 v[232:233], off
	s_waitcnt vmcnt(8)
	s_waitcnt lgkmcnt(0)
	s_barrier
	s_setprio 1
	v_mfma_f32_16x16x32_bf16 v[60:63], v[132:135], v[186:189], v[60:63]
	v_mfma_f32_16x16x32_bf16 v[56:59], v[140:143], v[186:189], v[56:59]
	v_mfma_f32_16x16x32_bf16 v[52:55], v[132:135], v[194:197], v[52:55]
	v_mfma_f32_16x16x32_bf16 v[48:51], v[140:143], v[194:197], v[48:51]
	v_mfma_f32_16x16x32_bf16 v[44:47], v[132:135], v[214:217], v[44:47]
	v_mfma_f32_16x16x32_bf16 v[40:43], v[140:143], v[214:217], v[40:43]
	v_mfma_f32_16x16x32_bf16 v[36:39], v[132:135], v[222:225], v[36:39]
	v_mfma_f32_16x16x32_bf16 v[32:35], v[140:143], v[222:225], v[32:35]
	v_mfma_f32_16x16x32_bf16 v[60:63], v[136:139], v[190:193], v[60:63]
	v_mfma_f32_16x16x32_bf16 v[56:59], v[166:169], v[190:193], v[56:59]
	v_mfma_f32_16x16x32_bf16 v[52:55], v[136:139], v[210:213], v[52:55]
	v_mfma_f32_16x16x32_bf16 v[48:51], v[166:169], v[210:213], v[48:51]
	v_mfma_f32_16x16x32_bf16 v[44:47], v[136:139], v[218:221], v[44:47]
	v_mfma_f32_16x16x32_bf16 v[40:43], v[166:169], v[218:221], v[40:43]
	v_mfma_f32_16x16x32_bf16 v[36:39], v[136:139], v[226:229], v[36:39]
	v_mfma_f32_16x16x32_bf16 v[32:35], v[166:169], v[226:229], v[32:35]
	v_mfma_f32_16x16x32_bf16 v[28:31], v[170:173], v[186:189], v[28:31]
	v_mfma_f32_16x16x32_bf16 v[24:27], v[178:181], v[186:189], v[24:27]
	v_mfma_f32_16x16x32_bf16 v[20:23], v[170:173], v[194:197], v[20:23]
	v_mfma_f32_16x16x32_bf16 v[16:19], v[178:181], v[194:197], v[16:19]
	v_mfma_f32_16x16x32_bf16 v[12:15], v[170:173], v[214:217], v[12:15]
	v_mfma_f32_16x16x32_bf16 v[8:11], v[178:181], v[214:217], v[8:11]
	v_mfma_f32_16x16x32_bf16 v[4:7], v[170:173], v[222:225], v[4:7]
	v_mfma_f32_16x16x32_bf16 v[0:3], v[178:181], v[222:225], v[0:3]
	v_mfma_f32_16x16x32_bf16 v[28:31], v[174:177], v[190:193], v[28:31]
	v_mfma_f32_16x16x32_bf16 v[24:27], v[182:185], v[190:193], v[24:27]
	v_mfma_f32_16x16x32_bf16 v[20:23], v[174:177], v[210:213], v[20:23]
	v_mfma_f32_16x16x32_bf16 v[16:19], v[182:185], v[210:213], v[16:19]
	v_mfma_f32_16x16x32_bf16 v[12:15], v[174:177], v[218:221], v[12:15]
	v_mfma_f32_16x16x32_bf16 v[8:11], v[182:185], v[218:221], v[8:11]
	v_mfma_f32_16x16x32_bf16 v[4:7], v[174:177], v[226:229], v[4:7]
	v_mfma_f32_16x16x32_bf16 v[0:3], v[182:185], v[226:229], v[0:3]
	s_setprio 0
	s_barrier
	s_add_i32 s72, 0, 0x18000
	v_add_u32_e32 v156, s72, v159
	s_add_i32 s73, 0, 0x1c000
	ds_read_b128 v[132:135], v156
	ds_read_b128 v[136:139], v156 offset:1024
	ds_read_b128 v[140:143], v156 offset:2048
	ds_read_b128 v[166:169], v156 offset:3072
	v_add_u32_e32 v156, s73, v159
	ds_read_b128 v[170:173], v156
	ds_read_b128 v[174:177], v156 offset:1024
	ds_read_b128 v[178:181], v156 offset:2048
	ds_read_b128 v[182:185], v156 offset:3072
	s_add_u32 s44, s44, 0x80000
	s_addc_u32 s45, s45, 0
	s_mov_b32 m0, s49
	v_lshl_add_u64 v[248:249], s[44:45], 0, v[144:145]
	ds_read_b128 v[186:189], v165 offset:32768
	ds_read_b128 v[190:193], v165 offset:33792
	ds_read_b128 v[194:197], v165 offset:34816
	ds_read_b128 v[210:213], v165 offset:35840
	ds_read_b128 v[214:217], v165 offset:36864
	ds_read_b128 v[218:221], v165 offset:37888
	ds_read_b128 v[222:225], v165 offset:38912
	ds_read_b128 v[226:229], v165 offset:39936
	global_load_lds_dwordx4 v[248:249], off
	v_lshl_add_u64 v[248:249], s[44:45], 0, v[146:147]
	s_mov_b32 m0, s50
	s_nop 0
	global_load_lds_dwordx4 v[248:249], off
	s_waitcnt vmcnt(8)
	s_waitcnt lgkmcnt(0)
	s_barrier
	s_setprio 1
	v_mfma_f32_16x16x32_bf16 v[124:127], v[132:135], v[186:189], v[124:127]
	v_mfma_f32_16x16x32_bf16 v[120:123], v[140:143], v[186:189], v[120:123]
	v_mfma_f32_16x16x32_bf16 v[116:119], v[132:135], v[194:197], v[116:119]
	v_mfma_f32_16x16x32_bf16 v[112:115], v[140:143], v[194:197], v[112:115]
	v_mfma_f32_16x16x32_bf16 v[108:111], v[132:135], v[214:217], v[108:111]
	v_mfma_f32_16x16x32_bf16 v[104:107], v[140:143], v[214:217], v[104:107]
	v_mfma_f32_16x16x32_bf16 v[100:103], v[132:135], v[222:225], v[100:103]
	v_mfma_f32_16x16x32_bf16 v[96:99], v[140:143], v[222:225], v[96:99]
	v_mfma_f32_16x16x32_bf16 v[124:127], v[136:139], v[190:193], v[124:127]
	v_mfma_f32_16x16x32_bf16 v[120:123], v[166:169], v[190:193], v[120:123]
	v_mfma_f32_16x16x32_bf16 v[116:119], v[136:139], v[210:213], v[116:119]
	v_mfma_f32_16x16x32_bf16 v[112:115], v[166:169], v[210:213], v[112:115]
	v_mfma_f32_16x16x32_bf16 v[108:111], v[136:139], v[218:221], v[108:111]
	v_mfma_f32_16x16x32_bf16 v[104:107], v[166:169], v[218:221], v[104:107]
	v_mfma_f32_16x16x32_bf16 v[100:103], v[136:139], v[226:229], v[100:103]
	v_mfma_f32_16x16x32_bf16 v[96:99], v[166:169], v[226:229], v[96:99]
	v_mfma_f32_16x16x32_bf16 v[92:95], v[170:173], v[186:189], v[92:95]
	v_mfma_f32_16x16x32_bf16 v[88:91], v[178:181], v[186:189], v[88:91]
	v_mfma_f32_16x16x32_bf16 v[84:87], v[170:173], v[194:197], v[84:87]
	v_mfma_f32_16x16x32_bf16 v[80:83], v[178:181], v[194:197], v[80:83]
	v_mfma_f32_16x16x32_bf16 v[76:79], v[170:173], v[214:217], v[76:79]
	v_mfma_f32_16x16x32_bf16 v[72:75], v[178:181], v[214:217], v[72:75]
	v_mfma_f32_16x16x32_bf16 v[68:71], v[170:173], v[222:225], v[68:71]
	v_mfma_f32_16x16x32_bf16 v[64:67], v[178:181], v[222:225], v[64:67]
	v_mfma_f32_16x16x32_bf16 v[92:95], v[174:177], v[190:193], v[92:95]
	v_mfma_f32_16x16x32_bf16 v[88:91], v[182:185], v[190:193], v[88:91]
	v_mfma_f32_16x16x32_bf16 v[84:87], v[174:177], v[210:213], v[84:87]
	v_mfma_f32_16x16x32_bf16 v[80:83], v[182:185], v[210:213], v[80:83]
	v_mfma_f32_16x16x32_bf16 v[76:79], v[174:177], v[218:221], v[76:79]
	v_mfma_f32_16x16x32_bf16 v[72:75], v[182:185], v[218:221], v[72:75]
	v_mfma_f32_16x16x32_bf16 v[68:71], v[174:177], v[226:229], v[68:71]
	v_mfma_f32_16x16x32_bf16 v[64:67], v[182:185], v[226:229], v[64:67]
	s_setprio 0
	s_barrier
	s_add_i32 s44, s72, s29
	v_lshl_add_u64 v[154:155], v[154:155], 0, s[12:13]
	s_mov_b32 m0, s44
	ds_read_b128 v[186:189], v165 offset:49152
	ds_read_b128 v[190:193], v165 offset:50176
	ds_read_b128 v[194:197], v165 offset:51200
	ds_read_b128 v[210:213], v165 offset:52224
	ds_read_b128 v[214:217], v165 offset:53248
	ds_read_b128 v[218:221], v165 offset:54272
	ds_read_b128 v[222:225], v165 offset:55296
	ds_read_b128 v[226:229], v165 offset:56320
	global_load_lds_dwordx4 v[154:155], off
	s_add_i32 m0, s44, 0x2000
	s_add_u32 s36, s36, 0x80080
	v_lshl_add_u64 v[154:155], v[198:199], 0, s[12:13]
	s_addc_u32 s37, s37, 0
	s_add_i32 s44, s73, s29
	global_load_lds_dwordx4 v[154:155], off
	v_lshl_add_u64 v[154:155], s[36:37], 0, v[204:205]
	s_mov_b32 m0, s44
	s_nop 0
	global_load_lds_dwordx4 v[154:155], off
	v_lshl_add_u64 v[154:155], s[36:37], 0, v[148:149]
	s_add_i32 m0, s44, 0x2000
	s_nop 0
	global_load_lds_dwordx4 v[154:155], off
	v_lshl_add_u64 v[154:155], v[230:231], 0, s[12:13]
	s_mov_b32 m0, s54
	s_nop 0
	global_load_lds_dwordx4 v[154:155], off
	v_lshl_add_u64 v[154:155], v[232:233], 0, s[12:13]
	s_mov_b32 m0, s55
	s_nop 0
	global_load_lds_dwordx4 v[154:155], off
	s_waitcnt vmcnt(8)
	s_waitcnt lgkmcnt(0)
	s_barrier
	s_setprio 1
	v_mfma_f32_16x16x32_bf16 v[60:63], v[132:135], v[186:189], v[60:63]
	v_mfma_f32_16x16x32_bf16 v[56:59], v[140:143], v[186:189], v[56:59]
	v_mfma_f32_16x16x32_bf16 v[52:55], v[132:135], v[194:197], v[52:55]
	v_mfma_f32_16x16x32_bf16 v[48:51], v[140:143], v[194:197], v[48:51]
	v_mfma_f32_16x16x32_bf16 v[44:47], v[132:135], v[214:217], v[44:47]
	v_mfma_f32_16x16x32_bf16 v[40:43], v[140:143], v[214:217], v[40:43]
	v_mfma_f32_16x16x32_bf16 v[36:39], v[132:135], v[222:225], v[36:39]
	v_mfma_f32_16x16x32_bf16 v[32:35], v[140:143], v[222:225], v[32:35]
	v_mfma_f32_16x16x32_bf16 v[60:63], v[136:139], v[190:193], v[60:63]
	v_mfma_f32_16x16x32_bf16 v[56:59], v[166:169], v[190:193], v[56:59]
	v_mfma_f32_16x16x32_bf16 v[52:55], v[136:139], v[210:213], v[52:55]
	v_mfma_f32_16x16x32_bf16 v[48:51], v[166:169], v[210:213], v[48:51]
	v_mfma_f32_16x16x32_bf16 v[44:47], v[136:139], v[218:221], v[44:47]
	v_mfma_f32_16x16x32_bf16 v[40:43], v[166:169], v[218:221], v[40:43]
	v_mfma_f32_16x16x32_bf16 v[36:39], v[136:139], v[226:229], v[36:39]
	v_mfma_f32_16x16x32_bf16 v[32:35], v[166:169], v[226:229], v[32:35]
	v_mfma_f32_16x16x32_bf16 v[28:31], v[170:173], v[186:189], v[28:31]
	v_mfma_f32_16x16x32_bf16 v[24:27], v[178:181], v[186:189], v[24:27]
	v_mfma_f32_16x16x32_bf16 v[20:23], v[170:173], v[194:197], v[20:23]
	v_mfma_f32_16x16x32_bf16 v[16:19], v[178:181], v[194:197], v[16:19]
	v_mfma_f32_16x16x32_bf16 v[12:15], v[170:173], v[214:217], v[12:15]
	v_mfma_f32_16x16x32_bf16 v[8:11], v[178:181], v[214:217], v[8:11]
	v_mfma_f32_16x16x32_bf16 v[4:7], v[170:173], v[222:225], v[4:7]
	v_mfma_f32_16x16x32_bf16 v[0:3], v[178:181], v[222:225], v[0:3]
	v_mfma_f32_16x16x32_bf16 v[28:31], v[174:177], v[190:193], v[28:31]
	v_mfma_f32_16x16x32_bf16 v[24:27], v[182:185], v[190:193], v[24:27]
	v_mfma_f32_16x16x32_bf16 v[20:23], v[174:177], v[210:213], v[20:23]
	v_mfma_f32_16x16x32_bf16 v[16:19], v[182:185], v[210:213], v[16:19]
	v_mfma_f32_16x16x32_bf16 v[12:15], v[174:177], v[218:221], v[12:15]
	v_mfma_f32_16x16x32_bf16 v[8:11], v[182:185], v[218:221], v[8:11]
	v_mfma_f32_16x16x32_bf16 v[4:7], v[174:177], v[226:229], v[4:7]
	v_mfma_f32_16x16x32_bf16 v[0:3], v[182:185], v[226:229], v[0:3]
	s_setprio 0
	s_barrier
	s_add_i32 s71, s71, 2
	s_add_u32 s0, s0, 0x100
	s_addc_u32 s1, s1, 0
	s_cmp_gt_u32 s71, 29
	s_cbranch_scc0 .LBB0_318

.LBB0_361:
	s_add_u32 s54, s0, 0x100
	s_addc_u32 s55, s1, 0
	s_ashr_i32 s11, s10, 31
	s_lshl_b64 s[14:15], s[10:11], 20
	s_add_u32 s20, s16, s14
	s_addc_u32 s21, s17, s15
	s_and_b64 s[14:15], s[64:65], exec
	s_cselect_b32 s11, s21, s3
	s_cselect_b32 s22, s20, s2
	s_ashr_i32 s9, s8, 31
	s_lshl_b64 s[14:15], s[8:9], 20
	s_add_u32 s14, s39, s14
	s_addc_u32 s15, s40, s15
	s_and_b64 s[28:29], s[64:65], exec
	s_cselect_b32 s9, s15, s1
	s_cselect_b32 s25, s14, s0
	s_add_u32 s0, s2, 0x80080
	s_addc_u32 s1, s3, 0
	v_lshl_add_u64 v[138:139], s[0:1], 0, v[134:135]
	s_waitcnt lgkmcnt(0)
	v_lshl_add_u64 v[140:141], s[0:1], 0, v[136:137]
	s_mov_b32 s28, -2
	s_mov_b64 s[0:1], 0
	s_add_u32 s29, s2, s0
	s_addc_u32 s34, s3, s1
	s_add_u32 s29, s29, 0x100
	s_addc_u32 s34, s34, 0
	s_add_u32 s56, s54, s0
	s_addc_u32 s35, s55, s1
	s_add_i32 s57, 0, 0x10000
	s_cmpk_eq_i32 s0, 0xf00
	s_cselect_b32 s37, s11, s34
	s_cselect_b32 s36, s22, s29
	v_add_u32_e32 v150, s57, v154
	s_cselect_b32 s35, s9, s35
	s_cselect_b32 s34, s25, s56
	s_add_i32 s29, 0, 0x14000
	ds_read_b128 v[142:145], v150
	ds_read_b128 v[146:149], v150 offset:1024
	ds_read_b128 v[160:163], v150 offset:2048
	ds_read_b128 v[164:167], v150 offset:3072
	v_add_u32_e32 v150, s29, v154
	ds_read_b128 v[168:171], v150
	ds_read_b128 v[172:175], v150 offset:1024
	ds_read_b128 v[176:179], v150 offset:2048
	ds_read_b128 v[180:183], v150 offset:3072
	v_lshl_add_u64 v[150:151], v[138:139], 0, s[0:1]
	s_add_i32 m0, s41, 0xc000
	ds_read_b128 v[184:187], v159
	ds_read_b128 v[188:191], v159 offset:1024
	ds_read_b128 v[192:195], v159 offset:2048
	ds_read_b128 v[196:199], v159 offset:3072
	ds_read_b128 v[210:213], v159 offset:4096
	ds_read_b128 v[214:217], v159 offset:5120
	ds_read_b128 v[218:221], v159 offset:6144
	ds_read_b128 v[222:225], v159 offset:7168
	global_load_lds_dwordx4 v[150:151], off
	v_lshl_add_u64 v[150:151], v[140:141], 0, s[0:1]
	s_add_i32 m0, s41, 0xe000
	s_nop 0
	global_load_lds_dwordx4 v[150:151], off
	s_waitcnt vmcnt(8)
	s_waitcnt lgkmcnt(0)
	s_barrier
	s_setprio 1
	v_mfma_f32_16x16x32_bf16 v[124:127], v[142:145], v[184:187], 0
	v_mfma_f32_16x16x32_bf16 v[120:123], v[160:163], v[184:187], 0
	v_mfma_f32_16x16x32_bf16 v[116:119], v[142:145], v[192:195], 0
	v_mfma_f32_16x16x32_bf16 v[112:115], v[160:163], v[192:195], 0
	v_mfma_f32_16x16x32_bf16 v[108:111], v[142:145], v[210:213], 0
	v_mfma_f32_16x16x32_bf16 v[104:107], v[160:163], v[210:213], 0
	v_mfma_f32_16x16x32_bf16 v[100:103], v[142:145], v[218:221], 0
	v_mfma_f32_16x16x32_bf16 v[96:99], v[160:163], v[218:221], 0
	v_mfma_f32_16x16x32_bf16 v[124:127], v[146:149], v[188:191], v[124:127]
	v_mfma_f32_16x16x32_bf16 v[120:123], v[164:167], v[188:191], v[120:123]
	v_mfma_f32_16x16x32_bf16 v[116:119], v[146:149], v[196:199], v[116:119]
	v_mfma_f32_16x16x32_bf16 v[112:115], v[164:167], v[196:199], v[112:115]
	v_mfma_f32_16x16x32_bf16 v[108:111], v[146:149], v[214:217], v[108:111]
	v_mfma_f32_16x16x32_bf16 v[104:107], v[164:167], v[214:217], v[104:107]
	v_mfma_f32_16x16x32_bf16 v[100:103], v[146:149], v[222:225], v[100:103]
	v_mfma_f32_16x16x32_bf16 v[96:99], v[164:167], v[222:225], v[96:99]
	v_mfma_f32_16x16x32_bf16 v[92:95], v[168:171], v[184:187], 0
	v_mfma_f32_16x16x32_bf16 v[88:91], v[176:179], v[184:187], 0
	v_mfma_f32_16x16x32_bf16 v[84:87], v[168:171], v[192:195], 0
	v_mfma_f32_16x16x32_bf16 v[80:83], v[176:179], v[192:195], 0
	v_mfma_f32_16x16x32_bf16 v[76:79], v[168:171], v[210:213], 0
	v_mfma_f32_16x16x32_bf16 v[72:75], v[176:179], v[210:213], 0
	v_mfma_f32_16x16x32_bf16 v[68:71], v[168:171], v[218:221], 0
	v_mfma_f32_16x16x32_bf16 v[64:67], v[176:179], v[218:221], 0
	v_mfma_f32_16x16x32_bf16 v[92:95], v[172:175], v[188:191], v[92:95]
	v_mfma_f32_16x16x32_bf16 v[88:91], v[180:183], v[188:191], v[88:91]
	v_mfma_f32_16x16x32_bf16 v[84:87], v[172:175], v[196:199], v[84:87]
	v_mfma_f32_16x16x32_bf16 v[80:83], v[180:183], v[196:199], v[80:83]
	v_mfma_f32_16x16x32_bf16 v[76:79], v[172:175], v[214:217], v[76:79]
	v_mfma_f32_16x16x32_bf16 v[72:75], v[180:183], v[214:217], v[72:75]
	v_mfma_f32_16x16x32_bf16 v[68:71], v[172:175], v[222:225], v[68:71]
	v_mfma_f32_16x16x32_bf16 v[64:67], v[180:183], v[222:225], v[64:67]
	s_setprio 0
	s_barrier
	s_add_i32 s56, s57, s38
	v_lshl_add_u64 v[150:151], s[34:35], 0, v[204:205]
	s_mov_b32 m0, s56
	ds_read_b128 v[184:187], v159 offset:16384
	ds_read_b128 v[188:191], v159 offset:17408
	ds_read_b128 v[192:195], v159 offset:18432
	ds_read_b128 v[196:199], v159 offset:19456
	ds_read_b128 v[210:213], v159 offset:20480
	ds_read_b128 v[214:217], v159 offset:21504
	ds_read_b128 v[218:221], v159 offset:22528
	ds_read_b128 v[222:225], v159 offset:23552
	global_load_lds_dwordx4 v[150:151], off
	s_add_i32 m0, s56, 0x2000
	s_add_u32 s56, s34, 0x80000
	v_lshl_add_u64 v[226:227], s[34:35], 0, v[128:129]
	s_addc_u32 s57, s35, 0
	s_add_i32 s29, s29, s38
	global_load_lds_dwordx4 v[226:227], off
	v_lshl_add_u64 v[228:229], s[56:57], 0, v[204:205]
	s_mov_b32 m0, s29
	v_lshl_add_u64 v[230:231], s[36:37], 0, v[130:131]
	global_load_lds_dwordx4 v[228:229], off
	v_lshl_add_u64 v[228:229], s[56:57], 0, v[128:129]
	s_add_i32 m0, s29, 0x2000
	s_nop 0
	global_load_lds_dwordx4 v[228:229], off
	v_lshl_add_u64 v[228:229], s[36:37], 0, v[132:133]
	s_mov_b32 m0, s41
	s_nop 0
	global_load_lds_dwordx4 v[228:229], off
	s_mov_b32 m0, s42
	s_nop 0
	global_load_lds_dwordx4 v[230:231], off
	s_waitcnt vmcnt(8)
	s_waitcnt lgkmcnt(0)
	s_barrier
	s_setprio 1
	v_mfma_f32_16x16x32_bf16 v[60:63], v[142:145], v[184:187], 0
	v_mfma_f32_16x16x32_bf16 v[56:59], v[160:163], v[184:187], 0
	v_mfma_f32_16x16x32_bf16 v[52:55], v[142:145], v[192:195], 0
	v_mfma_f32_16x16x32_bf16 v[48:51], v[160:163], v[192:195], 0
	v_mfma_f32_16x16x32_bf16 v[44:47], v[142:145], v[210:213], 0
	v_mfma_f32_16x16x32_bf16 v[40:43], v[160:163], v[210:213], 0
	v_mfma_f32_16x16x32_bf16 v[36:39], v[142:145], v[218:221], 0
	v_mfma_f32_16x16x32_bf16 v[32:35], v[160:163], v[218:221], 0
	v_mfma_f32_16x16x32_bf16 v[60:63], v[146:149], v[188:191], v[60:63]
	v_mfma_f32_16x16x32_bf16 v[56:59], v[164:167], v[188:191], v[56:59]
	v_mfma_f32_16x16x32_bf16 v[52:55], v[146:149], v[196:199], v[52:55]
	v_mfma_f32_16x16x32_bf16 v[48:51], v[164:167], v[196:199], v[48:51]
	v_mfma_f32_16x16x32_bf16 v[44:47], v[146:149], v[214:217], v[44:47]
	v_mfma_f32_16x16x32_bf16 v[40:43], v[164:167], v[214:217], v[40:43]
	v_mfma_f32_16x16x32_bf16 v[36:39], v[146:149], v[222:225], v[36:39]
	v_mfma_f32_16x16x32_bf16 v[32:35], v[164:167], v[222:225], v[32:35]
	v_mfma_f32_16x16x32_bf16 v[28:31], v[168:171], v[184:187], 0
	v_mfma_f32_16x16x32_bf16 v[24:27], v[176:179], v[184:187], 0
	v_mfma_f32_16x16x32_bf16 v[20:23], v[168:171], v[192:195], 0
	v_mfma_f32_16x16x32_bf16 v[16:19], v[176:179], v[192:195], 0
	v_mfma_f32_16x16x32_bf16 v[12:15], v[168:171], v[210:213], 0
	v_mfma_f32_16x16x32_bf16 v[8:11], v[176:179], v[210:213], 0
	v_mfma_f32_16x16x32_bf16 v[4:7], v[168:171], v[218:221], 0
	v_mfma_f32_16x16x32_bf16 v[0:3], v[176:179], v[218:221], 0
	v_mfma_f32_16x16x32_bf16 v[28:31], v[172:175], v[188:191], v[28:31]
	v_mfma_f32_16x16x32_bf16 v[24:27], v[180:183], v[188:191], v[24:27]
	v_mfma_f32_16x16x32_bf16 v[20:23], v[172:175], v[196:199], v[20:23]
	v_mfma_f32_16x16x32_bf16 v[16:19], v[180:183], v[196:199], v[16:19]
	v_mfma_f32_16x16x32_bf16 v[12:15], v[172:175], v[214:217], v[12:15]
	v_mfma_f32_16x16x32_bf16 v[8:11], v[180:183], v[214:217], v[8:11]
	v_mfma_f32_16x16x32_bf16 v[4:7], v[172:175], v[222:225], v[4:7]
	v_mfma_f32_16x16x32_bf16 v[0:3], v[180:183], v[222:225], v[0:3]
	s_setprio 0
	s_barrier
	s_add_i32 s29, 0, 0x18000
	v_add_u32_e32 v152, s29, v154
	s_add_i32 s56, 0, 0x1c000
	ds_read_b128 v[142:145], v152
	ds_read_b128 v[146:149], v152 offset:1024
	ds_read_b128 v[160:163], v152 offset:2048
	ds_read_b128 v[164:167], v152 offset:3072
	v_add_u32_e32 v152, s56, v154
	ds_read_b128 v[168:171], v152
	ds_read_b128 v[172:175], v152 offset:1024
	ds_read_b128 v[176:179], v152 offset:2048
	ds_read_b128 v[180:183], v152 offset:3072
	s_add_u32 s36, s36, 0x80000
	s_addc_u32 s37, s37, 0
	s_mov_b32 m0, s43
	v_lshl_add_u64 v[232:233], s[36:37], 0, v[132:133]
	ds_read_b128 v[184:187], v159 offset:32768
	ds_read_b128 v[188:191], v159 offset:33792
	ds_read_b128 v[192:195], v159 offset:34816
	ds_read_b128 v[196:199], v159 offset:35840
	ds_read_b128 v[210:213], v159 offset:36864
	ds_read_b128 v[214:217], v159 offset:37888
	ds_read_b128 v[218:221], v159 offset:38912
	ds_read_b128 v[222:225], v159 offset:39936
	global_load_lds_dwordx4 v[232:233], off
	v_lshl_add_u64 v[232:233], s[36:37], 0, v[130:131]
	s_mov_b32 m0, s44
	s_nop 0
	global_load_lds_dwordx4 v[232:233], off
	s_waitcnt vmcnt(8)
	s_waitcnt lgkmcnt(0)
	s_barrier
	s_setprio 1
	v_mfma_f32_16x16x32_bf16 v[124:127], v[142:145], v[184:187], v[124:127]
	v_mfma_f32_16x16x32_bf16 v[120:123], v[160:163], v[184:187], v[120:123]
	v_mfma_f32_16x16x32_bf16 v[116:119], v[142:145], v[192:195], v[116:119]
	v_mfma_f32_16x16x32_bf16 v[112:115], v[160:163], v[192:195], v[112:115]
	v_mfma_f32_16x16x32_bf16 v[108:111], v[142:145], v[210:213], v[108:111]
	v_mfma_f32_16x16x32_bf16 v[104:107], v[160:163], v[210:213], v[104:107]
	v_mfma_f32_16x16x32_bf16 v[100:103], v[142:145], v[218:221], v[100:103]
	v_mfma_f32_16x16x32_bf16 v[96:99], v[160:163], v[218:221], v[96:99]
	v_mfma_f32_16x16x32_bf16 v[124:127], v[146:149], v[188:191], v[124:127]
	v_mfma_f32_16x16x32_bf16 v[120:123], v[164:167], v[188:191], v[120:123]
	v_mfma_f32_16x16x32_bf16 v[116:119], v[146:149], v[196:199], v[116:119]
	v_mfma_f32_16x16x32_bf16 v[112:115], v[164:167], v[196:199], v[112:115]
	v_mfma_f32_16x16x32_bf16 v[108:111], v[146:149], v[214:217], v[108:111]
	v_mfma_f32_16x16x32_bf16 v[104:107], v[164:167], v[214:217], v[104:107]
	v_mfma_f32_16x16x32_bf16 v[100:103], v[146:149], v[222:225], v[100:103]
	v_mfma_f32_16x16x32_bf16 v[96:99], v[164:167], v[222:225], v[96:99]
	v_mfma_f32_16x16x32_bf16 v[92:95], v[168:171], v[184:187], v[92:95]
	v_mfma_f32_16x16x32_bf16 v[88:91], v[176:179], v[184:187], v[88:91]
	v_mfma_f32_16x16x32_bf16 v[84:87], v[168:171], v[192:195], v[84:87]
	v_mfma_f32_16x16x32_bf16 v[80:83], v[176:179], v[192:195], v[80:83]
	v_mfma_f32_16x16x32_bf16 v[76:79], v[168:171], v[210:213], v[76:79]
	v_mfma_f32_16x16x32_bf16 v[72:75], v[176:179], v[210:213], v[72:75]
	v_mfma_f32_16x16x32_bf16 v[68:71], v[168:171], v[218:221], v[68:71]
	v_mfma_f32_16x16x32_bf16 v[64:67], v[176:179], v[218:221], v[64:67]
	v_mfma_f32_16x16x32_bf16 v[92:95], v[172:175], v[188:191], v[92:95]
	v_mfma_f32_16x16x32_bf16 v[88:91], v[180:183], v[188:191], v[88:91]
	v_mfma_f32_16x16x32_bf16 v[84:87], v[172:175], v[196:199], v[84:87]
	v_mfma_f32_16x16x32_bf16 v[80:83], v[180:183], v[196:199], v[80:83]
	v_mfma_f32_16x16x32_bf16 v[76:79], v[172:175], v[214:217], v[76:79]
	v_mfma_f32_16x16x32_bf16 v[72:75], v[180:183], v[214:217], v[72:75]
	v_mfma_f32_16x16x32_bf16 v[68:71], v[172:175], v[222:225], v[68:71]
	v_mfma_f32_16x16x32_bf16 v[64:67], v[180:183], v[222:225], v[64:67]
	s_setprio 0
	s_barrier
	s_add_i32 s29, s29, s38
	v_lshl_add_u64 v[150:151], v[150:151], 0, s[12:13]
	s_mov_b32 m0, s29
	ds_read_b128 v[184:187], v159 offset:49152
	ds_read_b128 v[188:191], v159 offset:50176
	ds_read_b128 v[192:195], v159 offset:51200
	ds_read_b128 v[196:199], v159 offset:52224
	ds_read_b128 v[210:213], v159 offset:53248
	ds_read_b128 v[214:217], v159 offset:54272
	ds_read_b128 v[218:221], v159 offset:55296
	ds_read_b128 v[222:225], v159 offset:56320
	global_load_lds_dwordx4 v[150:151], off
	s_add_i32 m0, s29, 0x2000
	s_add_u32 s34, s34, 0x80080
	v_lshl_add_u64 v[150:151], v[226:227], 0, s[12:13]
	s_addc_u32 s35, s35, 0
	s_add_i32 s29, s56, s38
	global_load_lds_dwordx4 v[150:151], off
	v_lshl_add_u64 v[150:151], s[34:35], 0, v[204:205]
	s_mov_b32 m0, s29
	s_nop 0
	global_load_lds_dwordx4 v[150:151], off
	v_lshl_add_u64 v[150:151], s[34:35], 0, v[128:129]
	s_add_i32 m0, s29, 0x2000
	s_nop 0
	global_load_lds_dwordx4 v[150:151], off
	v_lshl_add_u64 v[150:151], v[228:229], 0, s[12:13]
	s_mov_b32 m0, s46
	s_nop 0
	global_load_lds_dwordx4 v[150:151], off
	v_lshl_add_u64 v[150:151], v[230:231], 0, s[12:13]
	s_mov_b32 m0, s47
	s_nop 0
	global_load_lds_dwordx4 v[150:151], off
	s_waitcnt vmcnt(8)
	s_waitcnt lgkmcnt(0)
	s_barrier
	s_setprio 1
	v_mfma_f32_16x16x32_bf16 v[60:63], v[142:145], v[184:187], v[60:63]
	v_mfma_f32_16x16x32_bf16 v[56:59], v[160:163], v[184:187], v[56:59]
	v_mfma_f32_16x16x32_bf16 v[52:55], v[142:145], v[192:195], v[52:55]
	v_mfma_f32_16x16x32_bf16 v[48:51], v[160:163], v[192:195], v[48:51]
	v_mfma_f32_16x16x32_bf16 v[44:47], v[142:145], v[210:213], v[44:47]
	v_mfma_f32_16x16x32_bf16 v[40:43], v[160:163], v[210:213], v[40:43]
	v_mfma_f32_16x16x32_bf16 v[36:39], v[142:145], v[218:221], v[36:39]
	v_mfma_f32_16x16x32_bf16 v[32:35], v[160:163], v[218:221], v[32:35]
	v_mfma_f32_16x16x32_bf16 v[60:63], v[146:149], v[188:191], v[60:63]
	v_mfma_f32_16x16x32_bf16 v[56:59], v[164:167], v[188:191], v[56:59]
	v_mfma_f32_16x16x32_bf16 v[52:55], v[146:149], v[196:199], v[52:55]
	v_mfma_f32_16x16x32_bf16 v[48:51], v[164:167], v[196:199], v[48:51]
	v_mfma_f32_16x16x32_bf16 v[44:47], v[146:149], v[214:217], v[44:47]
	v_mfma_f32_16x16x32_bf16 v[40:43], v[164:167], v[214:217], v[40:43]
	v_mfma_f32_16x16x32_bf16 v[36:39], v[146:149], v[222:225], v[36:39]
	v_mfma_f32_16x16x32_bf16 v[32:35], v[164:167], v[222:225], v[32:35]
	v_mfma_f32_16x16x32_bf16 v[28:31], v[168:171], v[184:187], v[28:31]
	v_mfma_f32_16x16x32_bf16 v[24:27], v[176:179], v[184:187], v[24:27]
	v_mfma_f32_16x16x32_bf16 v[20:23], v[168:171], v[192:195], v[20:23]
	v_mfma_f32_16x16x32_bf16 v[16:19], v[176:179], v[192:195], v[16:19]
	v_mfma_f32_16x16x32_bf16 v[12:15], v[168:171], v[210:213], v[12:15]
	v_mfma_f32_16x16x32_bf16 v[8:11], v[176:179], v[210:213], v[8:11]
	v_mfma_f32_16x16x32_bf16 v[4:7], v[168:171], v[218:221], v[4:7]
	v_mfma_f32_16x16x32_bf16 v[0:3], v[176:179], v[218:221], v[0:3]
	v_mfma_f32_16x16x32_bf16 v[28:31], v[172:175], v[188:191], v[28:31]
	v_mfma_f32_16x16x32_bf16 v[24:27], v[180:183], v[188:191], v[24:27]
	v_mfma_f32_16x16x32_bf16 v[20:23], v[172:175], v[196:199], v[20:23]
	v_mfma_f32_16x16x32_bf16 v[16:19], v[180:183], v[196:199], v[16:19]
	v_mfma_f32_16x16x32_bf16 v[12:15], v[172:175], v[214:217], v[12:15]
	v_mfma_f32_16x16x32_bf16 v[8:11], v[180:183], v[214:217], v[8:11]
	v_mfma_f32_16x16x32_bf16 v[4:7], v[172:175], v[222:225], v[4:7]
	v_mfma_f32_16x16x32_bf16 v[0:3], v[180:183], v[222:225], v[0:3]
	s_setprio 0
	s_barrier
	s_add_i32 s28, s28, 2
	s_add_u32 s0, s0, 0x100
	s_addc_u32 s1, s1, 0
	s_cmp_gt_u32 s28, 29
	s_cbranch_scc1 .Lpeel_exit_362
.LBB0_362:
	s_add_u32 s29, s2, s0
	s_addc_u32 s34, s3, s1
	s_add_u32 s29, s29, 0x100
	s_addc_u32 s34, s34, 0
	s_add_u32 s56, s54, s0
	s_addc_u32 s35, s55, s1
	s_add_i32 s57, 0, 0x10000
	s_cmpk_eq_i32 s0, 0xf00
	s_cselect_b32 s37, s11, s34
	s_cselect_b32 s36, s22, s29
	v_add_u32_e32 v150, s57, v154
	s_cselect_b32 s35, s9, s35
	s_cselect_b32 s34, s25, s56
	s_add_i32 s29, 0, 0x14000
	ds_read_b128 v[142:145], v150
	ds_read_b128 v[146:149], v150 offset:1024
	ds_read_b128 v[160:163], v150 offset:2048
	ds_read_b128 v[164:167], v150 offset:3072
	v_add_u32_e32 v150, s29, v154
	ds_read_b128 v[168:171], v150
	ds_read_b128 v[172:175], v150 offset:1024
	ds_read_b128 v[176:179], v150 offset:2048
	ds_read_b128 v[180:183], v150 offset:3072
	v_lshl_add_u64 v[150:151], v[138:139], 0, s[0:1]
	s_add_i32 m0, s41, 0xc000
	ds_read_b128 v[184:187], v159
	ds_read_b128 v[188:191], v159 offset:1024
	ds_read_b128 v[192:195], v159 offset:2048
	ds_read_b128 v[196:199], v159 offset:3072
	ds_read_b128 v[210:213], v159 offset:4096
	ds_read_b128 v[214:217], v159 offset:5120
	ds_read_b128 v[218:221], v159 offset:6144
	ds_read_b128 v[222:225], v159 offset:7168
	global_load_lds_dwordx4 v[150:151], off
	v_lshl_add_u64 v[150:151], v[140:141], 0, s[0:1]
	s_add_i32 m0, s41, 0xe000
	s_nop 0
	global_load_lds_dwordx4 v[150:151], off
	s_waitcnt vmcnt(8)
	s_waitcnt lgkmcnt(0)
	s_barrier
	s_setprio 1
	v_mfma_f32_16x16x32_bf16 v[124:127], v[142:145], v[184:187], v[124:127]
	v_mfma_f32_16x16x32_bf16 v[120:123], v[160:163], v[184:187], v[120:123]
	v_mfma_f32_16x16x32_bf16 v[116:119], v[142:145], v[192:195], v[116:119]
	v_mfma_f32_16x16x32_bf16 v[112:115], v[160:163], v[192:195], v[112:115]
	v_mfma_f32_16x16x32_bf16 v[108:111], v[142:145], v[210:213], v[108:111]
	v_mfma_f32_16x16x32_bf16 v[104:107], v[160:163], v[210:213], v[104:107]
	v_mfma_f32_16x16x32_bf16 v[100:103], v[142:145], v[218:221], v[100:103]
	v_mfma_f32_16x16x32_bf16 v[96:99], v[160:163], v[218:221], v[96:99]
	v_mfma_f32_16x16x32_bf16 v[124:127], v[146:149], v[188:191], v[124:127]
	v_mfma_f32_16x16x32_bf16 v[120:123], v[164:167], v[188:191], v[120:123]
	v_mfma_f32_16x16x32_bf16 v[116:119], v[146:149], v[196:199], v[116:119]
	v_mfma_f32_16x16x32_bf16 v[112:115], v[164:167], v[196:199], v[112:115]
	v_mfma_f32_16x16x32_bf16 v[108:111], v[146:149], v[214:217], v[108:111]
	v_mfma_f32_16x16x32_bf16 v[104:107], v[164:167], v[214:217], v[104:107]
	v_mfma_f32_16x16x32_bf16 v[100:103], v[146:149], v[222:225], v[100:103]
	v_mfma_f32_16x16x32_bf16 v[96:99], v[164:167], v[222:225], v[96:99]
	v_mfma_f32_16x16x32_bf16 v[92:95], v[168:171], v[184:187], v[92:95]
	v_mfma_f32_16x16x32_bf16 v[88:91], v[176:179], v[184:187], v[88:91]
	v_mfma_f32_16x16x32_bf16 v[84:87], v[168:171], v[192:195], v[84:87]
	v_mfma_f32_16x16x32_bf16 v[80:83], v[176:179], v[192:195], v[80:83]
	v_mfma_f32_16x16x32_bf16 v[76:79], v[168:171], v[210:213], v[76:79]
	v_mfma_f32_16x16x32_bf16 v[72:75], v[176:179], v[210:213], v[72:75]
	v_mfma_f32_16x16x32_bf16 v[68:71], v[168:171], v[218:221], v[68:71]
	v_mfma_f32_16x16x32_bf16 v[64:67], v[176:179], v[218:221], v[64:67]
	v_mfma_f32_16x16x32_bf16 v[92:95], v[172:175], v[188:191], v[92:95]
	v_mfma_f32_16x16x32_bf16 v[88:91], v[180:183], v[188:191], v[88:91]
	v_mfma_f32_16x16x32_bf16 v[84:87], v[172:175], v[196:199], v[84:87]
	v_mfma_f32_16x16x32_bf16 v[80:83], v[180:183], v[196:199], v[80:83]
	v_mfma_f32_16x16x32_bf16 v[76:79], v[172:175], v[214:217], v[76:79]
	v_mfma_f32_16x16x32_bf16 v[72:75], v[180:183], v[214:217], v[72:75]
	v_mfma_f32_16x16x32_bf16 v[68:71], v[172:175], v[222:225], v[68:71]
	v_mfma_f32_16x16x32_bf16 v[64:67], v[180:183], v[222:225], v[64:67]
	s_setprio 0
	s_barrier
	s_add_i32 s56, s57, s38
	v_lshl_add_u64 v[150:151], s[34:35], 0, v[204:205]
	s_mov_b32 m0, s56
	ds_read_b128 v[184:187], v159 offset:16384
	ds_read_b128 v[188:191], v159 offset:17408
	ds_read_b128 v[192:195], v159 offset:18432
	ds_read_b128 v[196:199], v159 offset:19456
	ds_read_b128 v[210:213], v159 offset:20480
	ds_read_b128 v[214:217], v159 offset:21504
	ds_read_b128 v[218:221], v159 offset:22528
	ds_read_b128 v[222:225], v159 offset:23552
	global_load_lds_dwordx4 v[150:151], off
	s_add_i32 m0, s56, 0x2000
	s_add_u32 s56, s34, 0x80000
	v_lshl_add_u64 v[226:227], s[34:35], 0, v[128:129]
	s_addc_u32 s57, s35, 0
	s_add_i32 s29, s29, s38
	global_load_lds_dwordx4 v[226:227], off
	v_lshl_add_u64 v[228:229], s[56:57], 0, v[204:205]
	s_mov_b32 m0, s29
	v_lshl_add_u64 v[230:231], s[36:37], 0, v[130:131]
	global_load_lds_dwordx4 v[228:229], off
	v_lshl_add_u64 v[228:229], s[56:57], 0, v[128:129]
	s_add_i32 m0, s29, 0x2000
	s_nop 0
	global_load_lds_dwordx4 v[228:229], off
	v_lshl_add_u64 v[228:229], s[36:37], 0, v[132:133]
	s_mov_b32 m0, s41
	s_nop 0
	global_load_lds_dwordx4 v[228:229], off
	s_mov_b32 m0, s42
	s_nop 0
	global_load_lds_dwordx4 v[230:231], off
	s_waitcnt vmcnt(8)
	s_waitcnt lgkmcnt(0)
	s_barrier
	s_setprio 1
	v_mfma_f32_16x16x32_bf16 v[60:63], v[142:145], v[184:187], v[60:63]
	v_mfma_f32_16x16x32_bf16 v[56:59], v[160:163], v[184:187], v[56:59]
	v_mfma_f32_16x16x32_bf16 v[52:55], v[142:145], v[192:195], v[52:55]
	v_mfma_f32_16x16x32_bf16 v[48:51], v[160:163], v[192:195], v[48:51]
	v_mfma_f32_16x16x32_bf16 v[44:47], v[142:145], v[210:213], v[44:47]
	v_mfma_f32_16x16x32_bf16 v[40:43], v[160:163], v[210:213], v[40:43]
	v_mfma_f32_16x16x32_bf16 v[36:39], v[142:145], v[218:221], v[36:39]
	v_mfma_f32_16x16x32_bf16 v[32:35], v[160:163], v[218:221], v[32:35]
	v_mfma_f32_16x16x32_bf16 v[60:63], v[146:149], v[188:191], v[60:63]
	v_mfma_f32_16x16x32_bf16 v[56:59], v[164:167], v[188:191], v[56:59]
	v_mfma_f32_16x16x32_bf16 v[52:55], v[146:149], v[196:199], v[52:55]
	v_mfma_f32_16x16x32_bf16 v[48:51], v[164:167], v[196:199], v[48:51]
	v_mfma_f32_16x16x32_bf16 v[44:47], v[146:149], v[214:217], v[44:47]
	v_mfma_f32_16x16x32_bf16 v[40:43], v[164:167], v[214:217], v[40:43]
	v_mfma_f32_16x16x32_bf16 v[36:39], v[146:149], v[222:225], v[36:39]
	v_mfma_f32_16x16x32_bf16 v[32:35], v[164:167], v[222:225], v[32:35]
	v_mfma_f32_16x16x32_bf16 v[28:31], v[168:171], v[184:187], v[28:31]
	v_mfma_f32_16x16x32_bf16 v[24:27], v[176:179], v[184:187], v[24:27]
	v_mfma_f32_16x16x32_bf16 v[20:23], v[168:171], v[192:195], v[20:23]
	v_mfma_f32_16x16x32_bf16 v[16:19], v[176:179], v[192:195], v[16:19]
	v_mfma_f32_16x16x32_bf16 v[12:15], v[168:171], v[210:213], v[12:15]
	v_mfma_f32_16x16x32_bf16 v[8:11], v[176:179], v[210:213], v[8:11]
	v_mfma_f32_16x16x32_bf16 v[4:7], v[168:171], v[218:221], v[4:7]
	v_mfma_f32_16x16x32_bf16 v[0:3], v[176:179], v[218:221], v[0:3]
	v_mfma_f32_16x16x32_bf16 v[28:31], v[172:175], v[188:191], v[28:31]
	v_mfma_f32_16x16x32_bf16 v[24:27], v[180:183], v[188:191], v[24:27]
	v_mfma_f32_16x16x32_bf16 v[20:23], v[172:175], v[196:199], v[20:23]
	v_mfma_f32_16x16x32_bf16 v[16:19], v[180:183], v[196:199], v[16:19]
	v_mfma_f32_16x16x32_bf16 v[12:15], v[172:175], v[214:217], v[12:15]
	v_mfma_f32_16x16x32_bf16 v[8:11], v[180:183], v[214:217], v[8:11]
	v_mfma_f32_16x16x32_bf16 v[4:7], v[172:175], v[222:225], v[4:7]
	v_mfma_f32_16x16x32_bf16 v[0:3], v[180:183], v[222:225], v[0:3]
	s_setprio 0
	s_barrier
	s_add_i32 s29, 0, 0x18000
	v_add_u32_e32 v152, s29, v154
	s_add_i32 s56, 0, 0x1c000
	ds_read_b128 v[142:145], v152
	ds_read_b128 v[146:149], v152 offset:1024
	ds_read_b128 v[160:163], v152 offset:2048
	ds_read_b128 v[164:167], v152 offset:3072
	v_add_u32_e32 v152, s56, v154
	ds_read_b128 v[168:171], v152
	ds_read_b128 v[172:175], v152 offset:1024
	ds_read_b128 v[176:179], v152 offset:2048
	ds_read_b128 v[180:183], v152 offset:3072
	s_add_u32 s36, s36, 0x80000
	s_addc_u32 s37, s37, 0
	s_mov_b32 m0, s43
	v_lshl_add_u64 v[232:233], s[36:37], 0, v[132:133]
	ds_read_b128 v[184:187], v159 offset:32768
	ds_read_b128 v[188:191], v159 offset:33792
	ds_read_b128 v[192:195], v159 offset:34816
	ds_read_b128 v[196:199], v159 offset:35840
	ds_read_b128 v[210:213], v159 offset:36864
	ds_read_b128 v[214:217], v159 offset:37888
	ds_read_b128 v[218:221], v159 offset:38912
	ds_read_b128 v[222:225], v159 offset:39936
	global_load_lds_dwordx4 v[232:233], off
	v_lshl_add_u64 v[232:233], s[36:37], 0, v[130:131]
	s_mov_b32 m0, s44
	s_nop 0
	global_load_lds_dwordx4 v[232:233], off
	s_waitcnt vmcnt(8)
	s_waitcnt lgkmcnt(0)
	s_barrier
	s_setprio 1
	v_mfma_f32_16x16x32_bf16 v[124:127], v[142:145], v[184:187], v[124:127]
	v_mfma_f32_16x16x32_bf16 v[120:123], v[160:163], v[184:187], v[120:123]
	v_mfma_f32_16x16x32_bf16 v[116:119], v[142:145], v[192:195], v[116:119]
	v_mfma_f32_16x16x32_bf16 v[112:115], v[160:163], v[192:195], v[112:115]
	v_mfma_f32_16x16x32_bf16 v[108:111], v[142:145], v[210:213], v[108:111]
	v_mfma_f32_16x16x32_bf16 v[104:107], v[160:163], v[210:213], v[104:107]
	v_mfma_f32_16x16x32_bf16 v[100:103], v[142:145], v[218:221], v[100:103]
	v_mfma_f32_16x16x32_bf16 v[96:99], v[160:163], v[218:221], v[96:99]
	v_mfma_f32_16x16x32_bf16 v[124:127], v[146:149], v[188:191], v[124:127]
	v_mfma_f32_16x16x32_bf16 v[120:123], v[164:167], v[188:191], v[120:123]
	v_mfma_f32_16x16x32_bf16 v[116:119], v[146:149], v[196:199], v[116:119]
	v_mfma_f32_16x16x32_bf16 v[112:115], v[164:167], v[196:199], v[112:115]
	v_mfma_f32_16x16x32_bf16 v[108:111], v[146:149], v[214:217], v[108:111]
	v_mfma_f32_16x16x32_bf16 v[104:107], v[164:167], v[214:217], v[104:107]
	v_mfma_f32_16x16x32_bf16 v[100:103], v[146:149], v[222:225], v[100:103]
	v_mfma_f32_16x16x32_bf16 v[96:99], v[164:167], v[222:225], v[96:99]
	v_mfma_f32_16x16x32_bf16 v[92:95], v[168:171], v[184:187], v[92:95]
	v_mfma_f32_16x16x32_bf16 v[88:91], v[176:179], v[184:187], v[88:91]
	v_mfma_f32_16x16x32_bf16 v[84:87], v[168:171], v[192:195], v[84:87]
	v_mfma_f32_16x16x32_bf16 v[80:83], v[176:179], v[192:195], v[80:83]
	v_mfma_f32_16x16x32_bf16 v[76:79], v[168:171], v[210:213], v[76:79]
	v_mfma_f32_16x16x32_bf16 v[72:75], v[176:179], v[210:213], v[72:75]
	v_mfma_f32_16x16x32_bf16 v[68:71], v[168:171], v[218:221], v[68:71]
	v_mfma_f32_16x16x32_bf16 v[64:67], v[176:179], v[218:221], v[64:67]
	v_mfma_f32_16x16x32_bf16 v[92:95], v[172:175], v[188:191], v[92:95]
	v_mfma_f32_16x16x32_bf16 v[88:91], v[180:183], v[188:191], v[88:91]
	v_mfma_f32_16x16x32_bf16 v[84:87], v[172:175], v[196:199], v[84:87]
	v_mfma_f32_16x16x32_bf16 v[80:83], v[180:183], v[196:199], v[80:83]
	v_mfma_f32_16x16x32_bf16 v[76:79], v[172:175], v[214:217], v[76:79]
	v_mfma_f32_16x16x32_bf16 v[72:75], v[180:183], v[214:217], v[72:75]
	v_mfma_f32_16x16x32_bf16 v[68:71], v[172:175], v[222:225], v[68:71]
	v_mfma_f32_16x16x32_bf16 v[64:67], v[180:183], v[222:225], v[64:67]
	s_setprio 0
	s_barrier
	s_add_i32 s29, s29, s38
	v_lshl_add_u64 v[150:151], v[150:151], 0, s[12:13]
	s_mov_b32 m0, s29
	ds_read_b128 v[184:187], v159 offset:49152
	ds_read_b128 v[188:191], v159 offset:50176
	ds_read_b128 v[192:195], v159 offset:51200
	ds_read_b128 v[196:199], v159 offset:52224
	ds_read_b128 v[210:213], v159 offset:53248
	ds_read_b128 v[214:217], v159 offset:54272
	ds_read_b128 v[218:221], v159 offset:55296
	ds_read_b128 v[222:225], v159 offset:56320
	global_load_lds_dwordx4 v[150:151], off
	s_add_i32 m0, s29, 0x2000
	s_add_u32 s34, s34, 0x80080
	v_lshl_add_u64 v[150:151], v[226:227], 0, s[12:13]
	s_addc_u32 s35, s35, 0
	s_add_i32 s29, s56, s38
	global_load_lds_dwordx4 v[150:151], off
	v_lshl_add_u64 v[150:151], s[34:35], 0, v[204:205]
	s_mov_b32 m0, s29
	s_nop 0
	global_load_lds_dwordx4 v[150:151], off
	v_lshl_add_u64 v[150:151], s[34:35], 0, v[128:129]
	s_add_i32 m0, s29, 0x2000
	s_nop 0
	global_load_lds_dwordx4 v[150:151], off
	v_lshl_add_u64 v[150:151], v[228:229], 0, s[12:13]
	s_mov_b32 m0, s46
	s_nop 0
	global_load_lds_dwordx4 v[150:151], off
	v_lshl_add_u64 v[150:151], v[230:231], 0, s[12:13]
	s_mov_b32 m0, s47
	s_nop 0
	global_load_lds_dwordx4 v[150:151], off
	s_waitcnt vmcnt(8)
	s_waitcnt lgkmcnt(0)
	s_barrier
	s_setprio 1
	v_mfma_f32_16x16x32_bf16 v[60:63], v[142:145], v[184:187], v[60:63]
	v_mfma_f32_16x16x32_bf16 v[56:59], v[160:163], v[184:187], v[56:59]
	v_mfma_f32_16x16x32_bf16 v[52:55], v[142:145], v[192:195], v[52:55]
	v_mfma_f32_16x16x32_bf16 v[48:51], v[160:163], v[192:195], v[48:51]
	v_mfma_f32_16x16x32_bf16 v[44:47], v[142:145], v[210:213], v[44:47]
	v_mfma_f32_16x16x32_bf16 v[40:43], v[160:163], v[210:213], v[40:43]
	v_mfma_f32_16x16x32_bf16 v[36:39], v[142:145], v[218:221], v[36:39]
	v_mfma_f32_16x16x32_bf16 v[32:35], v[160:163], v[218:221], v[32:35]
	v_mfma_f32_16x16x32_bf16 v[60:63], v[146:149], v[188:191], v[60:63]
	v_mfma_f32_16x16x32_bf16 v[56:59], v[164:167], v[188:191], v[56:59]
	v_mfma_f32_16x16x32_bf16 v[52:55], v[146:149], v[196:199], v[52:55]
	v_mfma_f32_16x16x32_bf16 v[48:51], v[164:167], v[196:199], v[48:51]
	v_mfma_f32_16x16x32_bf16 v[44:47], v[146:149], v[214:217], v[44:47]
	v_mfma_f32_16x16x32_bf16 v[40:43], v[164:167], v[214:217], v[40:43]
	v_mfma_f32_16x16x32_bf16 v[36:39], v[146:149], v[222:225], v[36:39]
	v_mfma_f32_16x16x32_bf16 v[32:35], v[164:167], v[222:225], v[32:35]
	v_mfma_f32_16x16x32_bf16 v[28:31], v[168:171], v[184:187], v[28:31]
	v_mfma_f32_16x16x32_bf16 v[24:27], v[176:179], v[184:187], v[24:27]
	v_mfma_f32_16x16x32_bf16 v[20:23], v[168:171], v[192:195], v[20:23]
	v_mfma_f32_16x16x32_bf16 v[16:19], v[176:179], v[192:195], v[16:19]
	v_mfma_f32_16x16x32_bf16 v[12:15], v[168:171], v[210:213], v[12:15]
	v_mfma_f32_16x16x32_bf16 v[8:11], v[176:179], v[210:213], v[8:11]
	v_mfma_f32_16x16x32_bf16 v[4:7], v[168:171], v[218:221], v[4:7]
	v_mfma_f32_16x16x32_bf16 v[0:3], v[176:179], v[218:221], v[0:3]
	v_mfma_f32_16x16x32_bf16 v[28:31], v[172:175], v[188:191], v[28:31]
	v_mfma_f32_16x16x32_bf16 v[24:27], v[180:183], v[188:191], v[24:27]
	v_mfma_f32_16x16x32_bf16 v[20:23], v[172:175], v[196:199], v[20:23]
	v_mfma_f32_16x16x32_bf16 v[16:19], v[180:183], v[196:199], v[16:19]
	v_mfma_f32_16x16x32_bf16 v[12:15], v[172:175], v[214:217], v[12:15]
	v_mfma_f32_16x16x32_bf16 v[8:11], v[180:183], v[214:217], v[8:11]
	v_mfma_f32_16x16x32_bf16 v[4:7], v[172:175], v[222:225], v[4:7]
	v_mfma_f32_16x16x32_bf16 v[0:3], v[180:183], v[222:225], v[0:3]
	s_setprio 0
	s_barrier
	s_add_i32 s28, s28, 2
	s_add_u32 s0, s0, 0x100
	s_addc_u32 s1, s1, 0
	s_cmp_gt_u32 s28, 29
	s_cbranch_scc0 .LBB0_362
